# scan body: state pairs hold (row a,row b) of one column, dot products accumulate per-row sums directly - no lo+hi adds
# speedup vs baseline: 1.0089x; 1.0017x over previous
.Lsc_noprep:
	s_lshr_b32 s54, s33, s3
	s_and_b32 s53, s33, s52
	s_lshl_b32 s54, s54, 11
	s_mul_i32 s55, s53, s1
	s_add_u32 s51, s0, s54
	s_add_u32 s51, s51, s55
	s_cmp_lg_u32 s53, 0
	s_cbranch_scc1 .Lsc_noinit
	s_cmp_eq_u32 s38, 0
	s_cbranch_scc0 .Lsc_zinit
	s_lshr_b32 s55, s33, 4
	s_lshl_b32 s55, s55, 1
	s_lshr_b32 s56, s43, 4
	s_add_u32 s55, s55, s56
	s_lshl_b32 s55, s55, 2
	s_lshr_b32 s56, s42, 1
	s_add_u32 s55, s55, s56
	s_cmp_eq_u32 s38, 0
	s_cselect_b32 s54, s42, s55
	s_lshl_b32 s54, s54, 1
	s_add_u32 s54, s54, s44
	s_lshl_b32 s54, s54, 1
	s_add_u32 s54, s54, s50
	s_lshl_b32 s54, s54, 4
	s_add_u32 s54, s54, s46
	s_lshl_b32 s54, s54, 14
	s_add_u32 s30, s36, s54
	s_addc_u32 s31, s37, 0
	global_load_dwordx4 v[94:97], v3, s[30:31]
	global_load_dwordx4 v[98:101], v3, s[30:31] offset:16
	global_load_dwordx4 v[102:105], v3, s[30:31] offset:256
	global_load_dwordx4 v[106:109], v3, s[30:31] offset:272
	s_waitcnt vmcnt(0)
	v_mov_b32_e32 v6, v94
	v_mov_b32_e32 v7, v102
	v_mov_b32_e32 v8, v95
	v_mov_b32_e32 v9, v103
	v_mov_b32_e32 v10, v96
	v_mov_b32_e32 v11, v104
	v_mov_b32_e32 v12, v97
	v_mov_b32_e32 v13, v105
	v_mov_b32_e32 v14, v98
	v_mov_b32_e32 v15, v106
	v_mov_b32_e32 v16, v99
	v_mov_b32_e32 v17, v107
	v_mov_b32_e32 v18, v100
	v_mov_b32_e32 v19, v108
	v_mov_b32_e32 v20, v101
	v_mov_b32_e32 v21, v109
	s_branch .Lsc_noinit

.Lsc_noinit:
	s_waitcnt lgkmcnt(0)
	v_pk_mul_f32 v[22:23], v[6:7], v[52:53] op_sel:[0,0] op_sel_hi:[1,0]
	v_pk_mul_f32 v[30:31], v[68:69], v[92:93] op_sel:[0,0] op_sel_hi:[0,1]
	ds_read_b128 v[94:97], v47 offset:256
	v_pk_fma_f32 v[22:23], v[8:9], v[52:53], v[22:23] op_sel:[0,1,0] op_sel_hi:[1,1,1]
	v_pk_mul_f32 v[32:33], v[68:69], v[92:93] op_sel:[1,0] op_sel_hi:[1,1]
	ds_read_b128 v[98:101], v47 offset:272
	v_pk_fma_f32 v[22:23], v[10:11], v[54:55], v[22:23] op_sel:[0,0,0] op_sel_hi:[1,0,1]
	v_pk_mul_f32 v[34:35], v[70:71], v[92:93] op_sel:[0,0] op_sel_hi:[0,1]
	ds_read_b128 v[110:113], v47 offset:8448
	v_pk_fma_f32 v[22:23], v[12:13], v[54:55], v[22:23] op_sel:[0,1,0] op_sel_hi:[1,1,1]
	v_pk_mul_f32 v[36:37], v[70:71], v[92:93] op_sel:[1,0] op_sel_hi:[1,1]
	ds_read_b128 v[114:117], v47 offset:8464
	v_pk_fma_f32 v[22:23], v[14:15], v[56:57], v[22:23] op_sel:[0,0,0] op_sel_hi:[1,0,1]
	v_pk_mul_f32 v[38:39], v[72:73], v[92:93] op_sel:[0,0] op_sel_hi:[0,1]
	ds_read_b64 v[134:135], v48 offset:256
	v_pk_fma_f32 v[22:23], v[16:17], v[56:57], v[22:23] op_sel:[0,1,0] op_sel_hi:[1,1,1]
	v_pk_mul_f32 v[40:41], v[72:73], v[92:93] op_sel:[1,0] op_sel_hi:[1,1]
	ds_read_b128 v[126:129], v47 offset:16640
	v_pk_fma_f32 v[22:23], v[18:19], v[58:59], v[22:23] op_sel:[0,0,0] op_sel_hi:[1,0,1]
	v_pk_mul_f32 v[42:43], v[74:75], v[92:93] op_sel:[0,0] op_sel_hi:[0,1]
	ds_read_b128 v[130:133], v47 offset:16656
	v_pk_fma_f32 v[22:23], v[20:21], v[58:59], v[22:23] op_sel:[0,1,0] op_sel_hi:[1,1,1]
	v_pk_mul_f32 v[44:45], v[74:75], v[92:93] op_sel:[1,0] op_sel_hi:[1,1]
	ds_read_b128 v[102:105], v47 offset:4352
	v_pk_fma_f32 v[30:31], v[84:85], v[6:7], v[30:31] op_sel:[0,0,0] op_sel_hi:[0,1,1]
	v_pk_fma_f32 v[32:33], v[84:85], v[8:9], v[32:33] op_sel:[1,0,0] op_sel_hi:[1,1,1]
	ds_read_b128 v[106:109], v47 offset:4368
	v_pk_fma_f32 v[34:35], v[86:87], v[10:11], v[34:35] op_sel:[0,0,0] op_sel_hi:[0,1,1]
	v_pk_fma_f32 v[36:37], v[86:87], v[12:13], v[36:37] op_sel:[1,0,0] op_sel_hi:[1,1,1]
	ds_read_b128 v[118:121], v47 offset:12544
	v_add_f32_dpp v22, v22, v22 quad_perm:[1,0,3,2] row_mask:0xf bank_mask:0xf
	v_add_f32_dpp v23, v23, v23 quad_perm:[1,0,3,2] row_mask:0xf bank_mask:0xf
	ds_read_b128 v[122:125], v47 offset:12560
	v_pk_fma_f32 v[38:39], v[88:89], v[14:15], v[38:39] op_sel:[0,0,0] op_sel_hi:[0,1,1]
	v_pk_fma_f32 v[40:41], v[88:89], v[16:17], v[40:41] op_sel:[1,0,0] op_sel_hi:[1,1,1]
	v_add_f32_dpp v22, v22, v22 quad_perm:[2,3,0,1] row_mask:0xf bank_mask:0xf
	v_add_f32_dpp v23, v23, v23 quad_perm:[2,3,0,1] row_mask:0xf bank_mask:0xf
	v_pk_fma_f32 v[42:43], v[90:91], v[18:19], v[42:43] op_sel:[0,0,0] op_sel_hi:[0,1,1]
	v_pk_fma_f32 v[44:45], v[90:91], v[20:21], v[44:45] op_sel:[1,0,0] op_sel_hi:[1,1,1]
	v_add_f32_dpp v22, v22, v22 row_half_mirror row_mask:0xf bank_mask:0xf
	v_add_f32_dpp v23, v23, v23 row_half_mirror row_mask:0xf bank_mask:0xf
	v_pk_fma_f32 v[6:7], v[60:61], v[22:23], v[30:31] op_sel:[0,0,0] op_sel_hi:[0,1,1] neg_lo:[0,1,0] neg_hi:[0,1,0]
	v_pk_fma_f32 v[8:9], v[60:61], v[22:23], v[32:33] op_sel:[1,0,0] op_sel_hi:[1,1,1] neg_lo:[0,1,0] neg_hi:[0,1,0]
	v_pk_mul_f32 v[26:27], v[6:7], v[76:77] op_sel:[0,0] op_sel_hi:[1,0]
	v_pk_fma_f32 v[10:11], v[62:63], v[22:23], v[34:35] op_sel:[0,0,0] op_sel_hi:[0,1,1] neg_lo:[0,1,0] neg_hi:[0,1,0]
	v_pk_fma_f32 v[26:27], v[8:9], v[76:77], v[26:27] op_sel:[0,1,0] op_sel_hi:[1,1,1]
	v_pk_fma_f32 v[12:13], v[62:63], v[22:23], v[36:37] op_sel:[1,0,0] op_sel_hi:[1,1,1] neg_lo:[0,1,0] neg_hi:[0,1,0]
	v_pk_fma_f32 v[26:27], v[10:11], v[78:79], v[26:27] op_sel:[0,0,0] op_sel_hi:[1,0,1]
	v_pk_fma_f32 v[14:15], v[64:65], v[22:23], v[38:39] op_sel:[0,0,0] op_sel_hi:[0,1,1] neg_lo:[0,1,0] neg_hi:[0,1,0]
	v_pk_fma_f32 v[26:27], v[12:13], v[78:79], v[26:27] op_sel:[0,1,0] op_sel_hi:[1,1,1]
	v_pk_fma_f32 v[16:17], v[64:65], v[22:23], v[40:41] op_sel:[1,0,0] op_sel_hi:[1,1,1] neg_lo:[0,1,0] neg_hi:[0,1,0]
	v_pk_fma_f32 v[26:27], v[14:15], v[80:81], v[26:27] op_sel:[0,0,0] op_sel_hi:[1,0,1]
	v_pk_fma_f32 v[18:19], v[66:67], v[22:23], v[42:43] op_sel:[0,0,0] op_sel_hi:[0,1,1] neg_lo:[0,1,0] neg_hi:[0,1,0]
	v_pk_fma_f32 v[26:27], v[16:17], v[80:81], v[26:27] op_sel:[0,1,0] op_sel_hi:[1,1,1]
	v_pk_fma_f32 v[20:21], v[66:67], v[22:23], v[44:45] op_sel:[1,0,0] op_sel_hi:[1,1,1] neg_lo:[0,1,0] neg_hi:[0,1,0]
	v_pk_fma_f32 v[26:27], v[18:19], v[82:83], v[26:27] op_sel:[0,0,0] op_sel_hi:[1,0,1]
	s_nop 0
	v_pk_fma_f32 v[26:27], v[20:21], v[82:83], v[26:27] op_sel:[0,1,0] op_sel_hi:[1,1,1]
	s_waitcnt lgkmcnt(4)
	v_pk_mul_f32 v[22:23], v[6:7], v[94:95] op_sel:[0,0] op_sel_hi:[1,0]
	v_pk_mul_f32 v[30:31], v[110:111], v[134:135] op_sel:[0,0] op_sel_hi:[0,1]
	ds_read_b128 v[52:55], v47 offset:512
	v_pk_fma_f32 v[22:23], v[8:9], v[94:95], v[22:23] op_sel:[0,1,0] op_sel_hi:[1,1,1]
	v_pk_mul_f32 v[32:33], v[110:111], v[134:135] op_sel:[1,0] op_sel_hi:[1,1]
	ds_read_b128 v[56:59], v47 offset:528
	v_pk_fma_f32 v[22:23], v[10:11], v[96:97], v[22:23] op_sel:[0,0,0] op_sel_hi:[1,0,1]
	v_pk_mul_f32 v[34:35], v[112:113], v[134:135] op_sel:[0,0] op_sel_hi:[0,1]
	ds_read_b128 v[68:71], v47 offset:8704
	v_pk_fma_f32 v[22:23], v[12:13], v[96:97], v[22:23] op_sel:[0,1,0] op_sel_hi:[1,1,1]
	v_pk_mul_f32 v[36:37], v[112:113], v[134:135] op_sel:[1,0] op_sel_hi:[1,1]
	ds_read_b128 v[72:75], v47 offset:8720
	v_pk_fma_f32 v[22:23], v[14:15], v[98:99], v[22:23] op_sel:[0,0,0] op_sel_hi:[1,0,1]
	v_pk_mul_f32 v[38:39], v[114:115], v[134:135] op_sel:[0,0] op_sel_hi:[0,1]
	ds_read_b64 v[92:93], v48 offset:512
	v_pk_fma_f32 v[22:23], v[16:17], v[98:99], v[22:23] op_sel:[0,1,0] op_sel_hi:[1,1,1]
	v_pk_mul_f32 v[40:41], v[114:115], v[134:135] op_sel:[1,0] op_sel_hi:[1,1]
	ds_read_b128 v[84:87], v47 offset:16896
	v_pk_fma_f32 v[22:23], v[18:19], v[100:101], v[22:23] op_sel:[0,0,0] op_sel_hi:[1,0,1]
	v_pk_mul_f32 v[42:43], v[116:117], v[134:135] op_sel:[0,0] op_sel_hi:[0,1]
	ds_read_b128 v[88:91], v47 offset:16912
	v_pk_fma_f32 v[22:23], v[20:21], v[100:101], v[22:23] op_sel:[0,1,0] op_sel_hi:[1,1,1]
	v_pk_mul_f32 v[44:45], v[116:117], v[134:135] op_sel:[1,0] op_sel_hi:[1,1]
	ds_read_b128 v[60:63], v47 offset:4608
	v_pk_fma_f32 v[30:31], v[126:127], v[6:7], v[30:31] op_sel:[0,0,0] op_sel_hi:[0,1,1]
	v_pk_fma_f32 v[32:33], v[126:127], v[8:9], v[32:33] op_sel:[1,0,0] op_sel_hi:[1,1,1]
	ds_read_b128 v[64:67], v47 offset:4624
	v_pk_fma_f32 v[34:35], v[128:129], v[10:11], v[34:35] op_sel:[0,0,0] op_sel_hi:[0,1,1]
	v_pk_fma_f32 v[36:37], v[128:129], v[12:13], v[36:37] op_sel:[1,0,0] op_sel_hi:[1,1,1]
	ds_read_b128 v[76:79], v47 offset:12800
	v_add_f32_dpp v22, v22, v22 quad_perm:[1,0,3,2] row_mask:0xf bank_mask:0xf
	v_add_f32_dpp v23, v23, v23 quad_perm:[1,0,3,2] row_mask:0xf bank_mask:0xf
	ds_read_b128 v[80:83], v47 offset:12816
	v_add_f32_dpp v26, v26, v26 quad_perm:[1,0,3,2] row_mask:0xf bank_mask:0xf
	v_add_f32_dpp v27, v27, v27 quad_perm:[1,0,3,2] row_mask:0xf bank_mask:0xf
	v_pk_fma_f32 v[38:39], v[130:131], v[14:15], v[38:39] op_sel:[0,0,0] op_sel_hi:[0,1,1]
	v_pk_fma_f32 v[40:41], v[130:131], v[16:17], v[40:41] op_sel:[1,0,0] op_sel_hi:[1,1,1]
	v_add_f32_dpp v22, v22, v22 quad_perm:[2,3,0,1] row_mask:0xf bank_mask:0xf
	v_add_f32_dpp v23, v23, v23 quad_perm:[2,3,0,1] row_mask:0xf bank_mask:0xf
	v_add_f32_dpp v26, v26, v26 quad_perm:[2,3,0,1] row_mask:0xf bank_mask:0xf
	v_add_f32_dpp v27, v27, v27 quad_perm:[2,3,0,1] row_mask:0xf bank_mask:0xf
	v_pk_fma_f32 v[42:43], v[132:133], v[18:19], v[42:43] op_sel:[0,0,0] op_sel_hi:[0,1,1]
	v_pk_fma_f32 v[44:45], v[132:133], v[20:21], v[44:45] op_sel:[1,0,0] op_sel_hi:[1,1,1]
	v_add_f32_dpp v22, v22, v22 row_half_mirror row_mask:0xf bank_mask:0xf
	v_add_f32_dpp v23, v23, v23 row_half_mirror row_mask:0xf bank_mask:0xf
	v_add_f32_dpp v26, v26, v26 row_half_mirror row_mask:0xf bank_mask:0xf
	v_add_f32_dpp v27, v27, v27 row_half_mirror row_mask:0xf bank_mask:0xf
	s_waitcnt lgkmcnt(11)
	v_pk_fma_f32 v[6:7], v[102:103], v[22:23], v[30:31] op_sel:[0,0,0] op_sel_hi:[0,1,1] neg_lo:[0,1,0] neg_hi:[0,1,0]
	v_cvt_pk_f16_f32 v46, v26, v27
	v_pk_fma_f32 v[8:9], v[102:103], v[22:23], v[32:33] op_sel:[1,0,0] op_sel_hi:[1,1,1] neg_lo:[0,1,0] neg_hi:[0,1,0]
	v_pk_mul_f32 v[26:27], v[6:7], v[118:119] op_sel:[0,0] op_sel_hi:[1,0]
	v_pk_fma_f32 v[10:11], v[104:105], v[22:23], v[34:35] op_sel:[0,0,0] op_sel_hi:[0,1,1] neg_lo:[0,1,0] neg_hi:[0,1,0]
	v_pk_fma_f32 v[26:27], v[8:9], v[118:119], v[26:27] op_sel:[0,1,0] op_sel_hi:[1,1,1]
	v_pk_fma_f32 v[12:13], v[104:105], v[22:23], v[36:37] op_sel:[1,0,0] op_sel_hi:[1,1,1] neg_lo:[0,1,0] neg_hi:[0,1,0]
	v_pk_fma_f32 v[26:27], v[10:11], v[120:121], v[26:27] op_sel:[0,0,0] op_sel_hi:[1,0,1]
	v_pk_fma_f32 v[14:15], v[106:107], v[22:23], v[38:39] op_sel:[0,0,0] op_sel_hi:[0,1,1] neg_lo:[0,1,0] neg_hi:[0,1,0]
	v_pk_fma_f32 v[26:27], v[12:13], v[120:121], v[26:27] op_sel:[0,1,0] op_sel_hi:[1,1,1]
	v_pk_fma_f32 v[16:17], v[106:107], v[22:23], v[40:41] op_sel:[1,0,0] op_sel_hi:[1,1,1] neg_lo:[0,1,0] neg_hi:[0,1,0]
	v_pk_fma_f32 v[26:27], v[14:15], v[122:123], v[26:27] op_sel:[0,0,0] op_sel_hi:[1,0,1]
	v_pk_fma_f32 v[18:19], v[108:109], v[22:23], v[42:43] op_sel:[0,0,0] op_sel_hi:[0,1,1] neg_lo:[0,1,0] neg_hi:[0,1,0]
	v_pk_fma_f32 v[26:27], v[16:17], v[122:123], v[26:27] op_sel:[0,1,0] op_sel_hi:[1,1,1]
	v_pk_fma_f32 v[20:21], v[108:109], v[22:23], v[44:45] op_sel:[1,0,0] op_sel_hi:[1,1,1] neg_lo:[0,1,0] neg_hi:[0,1,0]
	v_pk_fma_f32 v[26:27], v[18:19], v[124:125], v[26:27] op_sel:[0,0,0] op_sel_hi:[1,0,1]
	ds_write_b32 v49, v46 offset:0
	v_pk_fma_f32 v[26:27], v[20:21], v[124:125], v[26:27] op_sel:[0,1,0] op_sel_hi:[1,1,1]
	s_waitcnt lgkmcnt(5)
	v_pk_mul_f32 v[22:23], v[6:7], v[52:53] op_sel:[0,0] op_sel_hi:[1,0]
	v_pk_mul_f32 v[30:31], v[68:69], v[92:93] op_sel:[0,0] op_sel_hi:[0,1]
	ds_read_b128 v[94:97], v47 offset:768
	v_pk_fma_f32 v[22:23], v[8:9], v[52:53], v[22:23] op_sel:[0,1,0] op_sel_hi:[1,1,1]
	v_pk_mul_f32 v[32:33], v[68:69], v[92:93] op_sel:[1,0] op_sel_hi:[1,1]
	ds_read_b128 v[98:101], v47 offset:784
	v_pk_fma_f32 v[22:23], v[10:11], v[54:55], v[22:23] op_sel:[0,0,0] op_sel_hi:[1,0,1]
	v_pk_mul_f32 v[34:35], v[70:71], v[92:93] op_sel:[0,0] op_sel_hi:[0,1]
	ds_read_b128 v[110:113], v47 offset:8960
	v_pk_fma_f32 v[22:23], v[12:13], v[54:55], v[22:23] op_sel:[0,1,0] op_sel_hi:[1,1,1]
	v_pk_mul_f32 v[36:37], v[70:71], v[92:93] op_sel:[1,0] op_sel_hi:[1,1]
	ds_read_b128 v[114:117], v47 offset:8976
	v_pk_fma_f32 v[22:23], v[14:15], v[56:57], v[22:23] op_sel:[0,0,0] op_sel_hi:[1,0,1]
	v_pk_mul_f32 v[38:39], v[72:73], v[92:93] op_sel:[0,0] op_sel_hi:[0,1]
	ds_read_b64 v[134:135], v48 offset:768
	v_pk_fma_f32 v[22:23], v[16:17], v[56:57], v[22:23] op_sel:[0,1,0] op_sel_hi:[1,1,1]
	v_pk_mul_f32 v[40:41], v[72:73], v[92:93] op_sel:[1,0] op_sel_hi:[1,1]
	ds_read_b128 v[126:129], v47 offset:17152
	v_pk_fma_f32 v[22:23], v[18:19], v[58:59], v[22:23] op_sel:[0,0,0] op_sel_hi:[1,0,1]
	v_pk_mul_f32 v[42:43], v[74:75], v[92:93] op_sel:[0,0] op_sel_hi:[0,1]
	ds_read_b128 v[130:133], v47 offset:17168
	v_pk_fma_f32 v[22:23], v[20:21], v[58:59], v[22:23] op_sel:[0,1,0] op_sel_hi:[1,1,1]
	v_pk_mul_f32 v[44:45], v[74:75], v[92:93] op_sel:[1,0] op_sel_hi:[1,1]
	ds_read_b128 v[102:105], v47 offset:4864
	v_pk_fma_f32 v[30:31], v[84:85], v[6:7], v[30:31] op_sel:[0,0,0] op_sel_hi:[0,1,1]
	v_pk_fma_f32 v[32:33], v[84:85], v[8:9], v[32:33] op_sel:[1,0,0] op_sel_hi:[1,1,1]
	ds_read_b128 v[106:109], v47 offset:4880
	v_pk_fma_f32 v[34:35], v[86:87], v[10:11], v[34:35] op_sel:[0,0,0] op_sel_hi:[0,1,1]
	v_pk_fma_f32 v[36:37], v[86:87], v[12:13], v[36:37] op_sel:[1,0,0] op_sel_hi:[1,1,1]
	ds_read_b128 v[118:121], v47 offset:13056
	v_add_f32_dpp v22, v22, v22 quad_perm:[1,0,3,2] row_mask:0xf bank_mask:0xf
	v_add_f32_dpp v23, v23, v23 quad_perm:[1,0,3,2] row_mask:0xf bank_mask:0xf
	ds_read_b128 v[122:125], v47 offset:13072
	v_add_f32_dpp v26, v26, v26 quad_perm:[1,0,3,2] row_mask:0xf bank_mask:0xf
	v_add_f32_dpp v27, v27, v27 quad_perm:[1,0,3,2] row_mask:0xf bank_mask:0xf
	v_pk_fma_f32 v[38:39], v[88:89], v[14:15], v[38:39] op_sel:[0,0,0] op_sel_hi:[0,1,1]
	v_pk_fma_f32 v[40:41], v[88:89], v[16:17], v[40:41] op_sel:[1,0,0] op_sel_hi:[1,1,1]
	v_add_f32_dpp v22, v22, v22 quad_perm:[2,3,0,1] row_mask:0xf bank_mask:0xf
	v_add_f32_dpp v23, v23, v23 quad_perm:[2,3,0,1] row_mask:0xf bank_mask:0xf
	v_add_f32_dpp v26, v26, v26 quad_perm:[2,3,0,1] row_mask:0xf bank_mask:0xf
	v_add_f32_dpp v27, v27, v27 quad_perm:[2,3,0,1] row_mask:0xf bank_mask:0xf
	v_pk_fma_f32 v[42:43], v[90:91], v[18:19], v[42:43] op_sel:[0,0,0] op_sel_hi:[0,1,1]
	v_pk_fma_f32 v[44:45], v[90:91], v[20:21], v[44:45] op_sel:[1,0,0] op_sel_hi:[1,1,1]
	v_add_f32_dpp v22, v22, v22 row_half_mirror row_mask:0xf bank_mask:0xf
	v_add_f32_dpp v23, v23, v23 row_half_mirror row_mask:0xf bank_mask:0xf
	v_add_f32_dpp v26, v26, v26 row_half_mirror row_mask:0xf bank_mask:0xf
	v_add_f32_dpp v27, v27, v27 row_half_mirror row_mask:0xf bank_mask:0xf
	s_waitcnt lgkmcnt(12)
	v_pk_fma_f32 v[6:7], v[60:61], v[22:23], v[30:31] op_sel:[0,0,0] op_sel_hi:[0,1,1] neg_lo:[0,1,0] neg_hi:[0,1,0]
	v_cvt_pk_f16_f32 v46, v26, v27
	v_pk_fma_f32 v[8:9], v[60:61], v[22:23], v[32:33] op_sel:[1,0,0] op_sel_hi:[1,1,1] neg_lo:[0,1,0] neg_hi:[0,1,0]
	v_pk_mul_f32 v[26:27], v[6:7], v[76:77] op_sel:[0,0] op_sel_hi:[1,0]
	v_pk_fma_f32 v[10:11], v[62:63], v[22:23], v[34:35] op_sel:[0,0,0] op_sel_hi:[0,1,1] neg_lo:[0,1,0] neg_hi:[0,1,0]
	v_pk_fma_f32 v[26:27], v[8:9], v[76:77], v[26:27] op_sel:[0,1,0] op_sel_hi:[1,1,1]
	v_pk_fma_f32 v[12:13], v[62:63], v[22:23], v[36:37] op_sel:[1,0,0] op_sel_hi:[1,1,1] neg_lo:[0,1,0] neg_hi:[0,1,0]
	v_pk_fma_f32 v[26:27], v[10:11], v[78:79], v[26:27] op_sel:[0,0,0] op_sel_hi:[1,0,1]
	v_pk_fma_f32 v[14:15], v[64:65], v[22:23], v[38:39] op_sel:[0,0,0] op_sel_hi:[0,1,1] neg_lo:[0,1,0] neg_hi:[0,1,0]
	v_pk_fma_f32 v[26:27], v[12:13], v[78:79], v[26:27] op_sel:[0,1,0] op_sel_hi:[1,1,1]
	v_pk_fma_f32 v[16:17], v[64:65], v[22:23], v[40:41] op_sel:[1,0,0] op_sel_hi:[1,1,1] neg_lo:[0,1,0] neg_hi:[0,1,0]
	v_pk_fma_f32 v[26:27], v[14:15], v[80:81], v[26:27] op_sel:[0,0,0] op_sel_hi:[1,0,1]
	v_pk_fma_f32 v[18:19], v[66:67], v[22:23], v[42:43] op_sel:[0,0,0] op_sel_hi:[0,1,1] neg_lo:[0,1,0] neg_hi:[0,1,0]
	v_pk_fma_f32 v[26:27], v[16:17], v[80:81], v[26:27] op_sel:[0,1,0] op_sel_hi:[1,1,1]
	v_pk_fma_f32 v[20:21], v[66:67], v[22:23], v[44:45] op_sel:[1,0,0] op_sel_hi:[1,1,1] neg_lo:[0,1,0] neg_hi:[0,1,0]
	v_pk_fma_f32 v[26:27], v[18:19], v[82:83], v[26:27] op_sel:[0,0,0] op_sel_hi:[1,0,1]
	ds_write_b32 v49, v46 offset:128
	v_pk_fma_f32 v[26:27], v[20:21], v[82:83], v[26:27] op_sel:[0,1,0] op_sel_hi:[1,1,1]
	s_waitcnt lgkmcnt(5)
	v_pk_mul_f32 v[22:23], v[6:7], v[94:95] op_sel:[0,0] op_sel_hi:[1,0]
	v_pk_mul_f32 v[30:31], v[110:111], v[134:135] op_sel:[0,0] op_sel_hi:[0,1]
	ds_read_b128 v[52:55], v47 offset:1024
	v_pk_fma_f32 v[22:23], v[8:9], v[94:95], v[22:23] op_sel:[0,1,0] op_sel_hi:[1,1,1]
	v_pk_mul_f32 v[32:33], v[110:111], v[134:135] op_sel:[1,0] op_sel_hi:[1,1]
	ds_read_b128 v[56:59], v47 offset:1040
	v_pk_fma_f32 v[22:23], v[10:11], v[96:97], v[22:23] op_sel:[0,0,0] op_sel_hi:[1,0,1]
	v_pk_mul_f32 v[34:35], v[112:113], v[134:135] op_sel:[0,0] op_sel_hi:[0,1]
	ds_read_b128 v[68:71], v47 offset:9216
	v_pk_fma_f32 v[22:23], v[12:13], v[96:97], v[22:23] op_sel:[0,1,0] op_sel_hi:[1,1,1]
	v_pk_mul_f32 v[36:37], v[112:113], v[134:135] op_sel:[1,0] op_sel_hi:[1,1]
	ds_read_b128 v[72:75], v47 offset:9232
	v_pk_fma_f32 v[22:23], v[14:15], v[98:99], v[22:23] op_sel:[0,0,0] op_sel_hi:[1,0,1]
	v_pk_mul_f32 v[38:39], v[114:115], v[134:135] op_sel:[0,0] op_sel_hi:[0,1]
	ds_read_b64 v[92:93], v48 offset:1024
	v_pk_fma_f32 v[22:23], v[16:17], v[98:99], v[22:23] op_sel:[0,1,0] op_sel_hi:[1,1,1]
	v_pk_mul_f32 v[40:41], v[114:115], v[134:135] op_sel:[1,0] op_sel_hi:[1,1]
	ds_read_b128 v[84:87], v47 offset:17408
	v_pk_fma_f32 v[22:23], v[18:19], v[100:101], v[22:23] op_sel:[0,0,0] op_sel_hi:[1,0,1]
	v_pk_mul_f32 v[42:43], v[116:117], v[134:135] op_sel:[0,0] op_sel_hi:[0,1]
	ds_read_b128 v[88:91], v47 offset:17424
	v_pk_fma_f32 v[22:23], v[20:21], v[100:101], v[22:23] op_sel:[0,1,0] op_sel_hi:[1,1,1]
	v_pk_mul_f32 v[44:45], v[116:117], v[134:135] op_sel:[1,0] op_sel_hi:[1,1]
	ds_read_b128 v[60:63], v47 offset:5120
	v_pk_fma_f32 v[30:31], v[126:127], v[6:7], v[30:31] op_sel:[0,0,0] op_sel_hi:[0,1,1]
	v_pk_fma_f32 v[32:33], v[126:127], v[8:9], v[32:33] op_sel:[1,0,0] op_sel_hi:[1,1,1]
	ds_read_b128 v[64:67], v47 offset:5136
	v_pk_fma_f32 v[34:35], v[128:129], v[10:11], v[34:35] op_sel:[0,0,0] op_sel_hi:[0,1,1]
	v_pk_fma_f32 v[36:37], v[128:129], v[12:13], v[36:37] op_sel:[1,0,0] op_sel_hi:[1,1,1]
	ds_read_b128 v[76:79], v47 offset:13312
	v_add_f32_dpp v22, v22, v22 quad_perm:[1,0,3,2] row_mask:0xf bank_mask:0xf
	v_add_f32_dpp v23, v23, v23 quad_perm:[1,0,3,2] row_mask:0xf bank_mask:0xf
	ds_read_b128 v[80:83], v47 offset:13328
	v_add_f32_dpp v26, v26, v26 quad_perm:[1,0,3,2] row_mask:0xf bank_mask:0xf
	v_add_f32_dpp v27, v27, v27 quad_perm:[1,0,3,2] row_mask:0xf bank_mask:0xf
	v_pk_fma_f32 v[38:39], v[130:131], v[14:15], v[38:39] op_sel:[0,0,0] op_sel_hi:[0,1,1]
	v_pk_fma_f32 v[40:41], v[130:131], v[16:17], v[40:41] op_sel:[1,0,0] op_sel_hi:[1,1,1]
	v_add_f32_dpp v22, v22, v22 quad_perm:[2,3,0,1] row_mask:0xf bank_mask:0xf
	v_add_f32_dpp v23, v23, v23 quad_perm:[2,3,0,1] row_mask:0xf bank_mask:0xf
	v_add_f32_dpp v26, v26, v26 quad_perm:[2,3,0,1] row_mask:0xf bank_mask:0xf
	v_add_f32_dpp v27, v27, v27 quad_perm:[2,3,0,1] row_mask:0xf bank_mask:0xf
	v_pk_fma_f32 v[42:43], v[132:133], v[18:19], v[42:43] op_sel:[0,0,0] op_sel_hi:[0,1,1]
	v_pk_fma_f32 v[44:45], v[132:133], v[20:21], v[44:45] op_sel:[1,0,0] op_sel_hi:[1,1,1]
	v_add_f32_dpp v22, v22, v22 row_half_mirror row_mask:0xf bank_mask:0xf
	v_add_f32_dpp v23, v23, v23 row_half_mirror row_mask:0xf bank_mask:0xf
	v_add_f32_dpp v26, v26, v26 row_half_mirror row_mask:0xf bank_mask:0xf
	v_add_f32_dpp v27, v27, v27 row_half_mirror row_mask:0xf bank_mask:0xf
	s_waitcnt lgkmcnt(12)
	v_pk_fma_f32 v[6:7], v[102:103], v[22:23], v[30:31] op_sel:[0,0,0] op_sel_hi:[0,1,1] neg_lo:[0,1,0] neg_hi:[0,1,0]
	v_cvt_pk_f16_f32 v46, v26, v27
	v_pk_fma_f32 v[8:9], v[102:103], v[22:23], v[32:33] op_sel:[1,0,0] op_sel_hi:[1,1,1] neg_lo:[0,1,0] neg_hi:[0,1,0]
	v_pk_mul_f32 v[26:27], v[6:7], v[118:119] op_sel:[0,0] op_sel_hi:[1,0]
	v_pk_fma_f32 v[10:11], v[104:105], v[22:23], v[34:35] op_sel:[0,0,0] op_sel_hi:[0,1,1] neg_lo:[0,1,0] neg_hi:[0,1,0]
	v_pk_fma_f32 v[26:27], v[8:9], v[118:119], v[26:27] op_sel:[0,1,0] op_sel_hi:[1,1,1]
	v_pk_fma_f32 v[12:13], v[104:105], v[22:23], v[36:37] op_sel:[1,0,0] op_sel_hi:[1,1,1] neg_lo:[0,1,0] neg_hi:[0,1,0]
	v_pk_fma_f32 v[26:27], v[10:11], v[120:121], v[26:27] op_sel:[0,0,0] op_sel_hi:[1,0,1]
	v_pk_fma_f32 v[14:15], v[106:107], v[22:23], v[38:39] op_sel:[0,0,0] op_sel_hi:[0,1,1] neg_lo:[0,1,0] neg_hi:[0,1,0]
	v_pk_fma_f32 v[26:27], v[12:13], v[120:121], v[26:27] op_sel:[0,1,0] op_sel_hi:[1,1,1]
	v_pk_fma_f32 v[16:17], v[106:107], v[22:23], v[40:41] op_sel:[1,0,0] op_sel_hi:[1,1,1] neg_lo:[0,1,0] neg_hi:[0,1,0]
	v_pk_fma_f32 v[26:27], v[14:15], v[122:123], v[26:27] op_sel:[0,0,0] op_sel_hi:[1,0,1]
	v_pk_fma_f32 v[18:19], v[108:109], v[22:23], v[42:43] op_sel:[0,0,0] op_sel_hi:[0,1,1] neg_lo:[0,1,0] neg_hi:[0,1,0]
	v_pk_fma_f32 v[26:27], v[16:17], v[122:123], v[26:27] op_sel:[0,1,0] op_sel_hi:[1,1,1]
	v_pk_fma_f32 v[20:21], v[108:109], v[22:23], v[44:45] op_sel:[1,0,0] op_sel_hi:[1,1,1] neg_lo:[0,1,0] neg_hi:[0,1,0]
	v_pk_fma_f32 v[26:27], v[18:19], v[124:125], v[26:27] op_sel:[0,0,0] op_sel_hi:[1,0,1]
	ds_write_b32 v49, v46 offset:256
	v_pk_fma_f32 v[26:27], v[20:21], v[124:125], v[26:27] op_sel:[0,1,0] op_sel_hi:[1,1,1]
	s_waitcnt lgkmcnt(5)
	v_pk_mul_f32 v[22:23], v[6:7], v[52:53] op_sel:[0,0] op_sel_hi:[1,0]
	v_pk_mul_f32 v[30:31], v[68:69], v[92:93] op_sel:[0,0] op_sel_hi:[0,1]
	ds_read_b128 v[94:97], v47 offset:1280
	v_pk_fma_f32 v[22:23], v[8:9], v[52:53], v[22:23] op_sel:[0,1,0] op_sel_hi:[1,1,1]
	v_pk_mul_f32 v[32:33], v[68:69], v[92:93] op_sel:[1,0] op_sel_hi:[1,1]
	ds_read_b128 v[98:101], v47 offset:1296
	v_pk_fma_f32 v[22:23], v[10:11], v[54:55], v[22:23] op_sel:[0,0,0] op_sel_hi:[1,0,1]
	v_pk_mul_f32 v[34:35], v[70:71], v[92:93] op_sel:[0,0] op_sel_hi:[0,1]
	ds_read_b128 v[110:113], v47 offset:9472
	v_pk_fma_f32 v[22:23], v[12:13], v[54:55], v[22:23] op_sel:[0,1,0] op_sel_hi:[1,1,1]
	v_pk_mul_f32 v[36:37], v[70:71], v[92:93] op_sel:[1,0] op_sel_hi:[1,1]
	ds_read_b128 v[114:117], v47 offset:9488
	v_pk_fma_f32 v[22:23], v[14:15], v[56:57], v[22:23] op_sel:[0,0,0] op_sel_hi:[1,0,1]
	v_pk_mul_f32 v[38:39], v[72:73], v[92:93] op_sel:[0,0] op_sel_hi:[0,1]
	ds_read_b64 v[134:135], v48 offset:1280
	v_pk_fma_f32 v[22:23], v[16:17], v[56:57], v[22:23] op_sel:[0,1,0] op_sel_hi:[1,1,1]
	v_pk_mul_f32 v[40:41], v[72:73], v[92:93] op_sel:[1,0] op_sel_hi:[1,1]
	ds_read_b128 v[126:129], v47 offset:17664
	v_pk_fma_f32 v[22:23], v[18:19], v[58:59], v[22:23] op_sel:[0,0,0] op_sel_hi:[1,0,1]
	v_pk_mul_f32 v[42:43], v[74:75], v[92:93] op_sel:[0,0] op_sel_hi:[0,1]
	ds_read_b128 v[130:133], v47 offset:17680
	v_pk_fma_f32 v[22:23], v[20:21], v[58:59], v[22:23] op_sel:[0,1,0] op_sel_hi:[1,1,1]
	v_pk_mul_f32 v[44:45], v[74:75], v[92:93] op_sel:[1,0] op_sel_hi:[1,1]
	ds_read_b128 v[102:105], v47 offset:5376
	v_pk_fma_f32 v[30:31], v[84:85], v[6:7], v[30:31] op_sel:[0,0,0] op_sel_hi:[0,1,1]
	v_pk_fma_f32 v[32:33], v[84:85], v[8:9], v[32:33] op_sel:[1,0,0] op_sel_hi:[1,1,1]
	ds_read_b128 v[106:109], v47 offset:5392
	v_pk_fma_f32 v[34:35], v[86:87], v[10:11], v[34:35] op_sel:[0,0,0] op_sel_hi:[0,1,1]
	v_pk_fma_f32 v[36:37], v[86:87], v[12:13], v[36:37] op_sel:[1,0,0] op_sel_hi:[1,1,1]
	ds_read_b128 v[118:121], v47 offset:13568
	v_add_f32_dpp v22, v22, v22 quad_perm:[1,0,3,2] row_mask:0xf bank_mask:0xf
	v_add_f32_dpp v23, v23, v23 quad_perm:[1,0,3,2] row_mask:0xf bank_mask:0xf
	ds_read_b128 v[122:125], v47 offset:13584
	v_add_f32_dpp v26, v26, v26 quad_perm:[1,0,3,2] row_mask:0xf bank_mask:0xf
	v_add_f32_dpp v27, v27, v27 quad_perm:[1,0,3,2] row_mask:0xf bank_mask:0xf
	v_pk_fma_f32 v[38:39], v[88:89], v[14:15], v[38:39] op_sel:[0,0,0] op_sel_hi:[0,1,1]
	v_pk_fma_f32 v[40:41], v[88:89], v[16:17], v[40:41] op_sel:[1,0,0] op_sel_hi:[1,1,1]
	v_add_f32_dpp v22, v22, v22 quad_perm:[2,3,0,1] row_mask:0xf bank_mask:0xf
	v_add_f32_dpp v23, v23, v23 quad_perm:[2,3,0,1] row_mask:0xf bank_mask:0xf
	v_add_f32_dpp v26, v26, v26 quad_perm:[2,3,0,1] row_mask:0xf bank_mask:0xf
	v_add_f32_dpp v27, v27, v27 quad_perm:[2,3,0,1] row_mask:0xf bank_mask:0xf
	v_pk_fma_f32 v[42:43], v[90:91], v[18:19], v[42:43] op_sel:[0,0,0] op_sel_hi:[0,1,1]
	v_pk_fma_f32 v[44:45], v[90:91], v[20:21], v[44:45] op_sel:[1,0,0] op_sel_hi:[1,1,1]
	v_add_f32_dpp v22, v22, v22 row_half_mirror row_mask:0xf bank_mask:0xf
	v_add_f32_dpp v23, v23, v23 row_half_mirror row_mask:0xf bank_mask:0xf
	v_add_f32_dpp v26, v26, v26 row_half_mirror row_mask:0xf bank_mask:0xf
	v_add_f32_dpp v27, v27, v27 row_half_mirror row_mask:0xf bank_mask:0xf
	s_waitcnt lgkmcnt(12)
	v_pk_fma_f32 v[6:7], v[60:61], v[22:23], v[30:31] op_sel:[0,0,0] op_sel_hi:[0,1,1] neg_lo:[0,1,0] neg_hi:[0,1,0]
	v_cvt_pk_f16_f32 v46, v26, v27
	v_pk_fma_f32 v[8:9], v[60:61], v[22:23], v[32:33] op_sel:[1,0,0] op_sel_hi:[1,1,1] neg_lo:[0,1,0] neg_hi:[0,1,0]
	v_pk_mul_f32 v[26:27], v[6:7], v[76:77] op_sel:[0,0] op_sel_hi:[1,0]
	v_pk_fma_f32 v[10:11], v[62:63], v[22:23], v[34:35] op_sel:[0,0,0] op_sel_hi:[0,1,1] neg_lo:[0,1,0] neg_hi:[0,1,0]
	v_pk_fma_f32 v[26:27], v[8:9], v[76:77], v[26:27] op_sel:[0,1,0] op_sel_hi:[1,1,1]
	v_pk_fma_f32 v[12:13], v[62:63], v[22:23], v[36:37] op_sel:[1,0,0] op_sel_hi:[1,1,1] neg_lo:[0,1,0] neg_hi:[0,1,0]
	v_pk_fma_f32 v[26:27], v[10:11], v[78:79], v[26:27] op_sel:[0,0,0] op_sel_hi:[1,0,1]
	v_pk_fma_f32 v[14:15], v[64:65], v[22:23], v[38:39] op_sel:[0,0,0] op_sel_hi:[0,1,1] neg_lo:[0,1,0] neg_hi:[0,1,0]
	v_pk_fma_f32 v[26:27], v[12:13], v[78:79], v[26:27] op_sel:[0,1,0] op_sel_hi:[1,1,1]
	v_pk_fma_f32 v[16:17], v[64:65], v[22:23], v[40:41] op_sel:[1,0,0] op_sel_hi:[1,1,1] neg_lo:[0,1,0] neg_hi:[0,1,0]
	v_pk_fma_f32 v[26:27], v[14:15], v[80:81], v[26:27] op_sel:[0,0,0] op_sel_hi:[1,0,1]
	v_pk_fma_f32 v[18:19], v[66:67], v[22:23], v[42:43] op_sel:[0,0,0] op_sel_hi:[0,1,1] neg_lo:[0,1,0] neg_hi:[0,1,0]
	v_pk_fma_f32 v[26:27], v[16:17], v[80:81], v[26:27] op_sel:[0,1,0] op_sel_hi:[1,1,1]
	v_pk_fma_f32 v[20:21], v[66:67], v[22:23], v[44:45] op_sel:[1,0,0] op_sel_hi:[1,1,1] neg_lo:[0,1,0] neg_hi:[0,1,0]
	v_pk_fma_f32 v[26:27], v[18:19], v[82:83], v[26:27] op_sel:[0,0,0] op_sel_hi:[1,0,1]
	ds_write_b32 v49, v46 offset:384
	v_pk_fma_f32 v[26:27], v[20:21], v[82:83], v[26:27] op_sel:[0,1,0] op_sel_hi:[1,1,1]
	s_waitcnt lgkmcnt(5)
	v_pk_mul_f32 v[22:23], v[6:7], v[94:95] op_sel:[0,0] op_sel_hi:[1,0]
	v_pk_mul_f32 v[30:31], v[110:111], v[134:135] op_sel:[0,0] op_sel_hi:[0,1]
	ds_read_b128 v[52:55], v47 offset:1536
	v_pk_fma_f32 v[22:23], v[8:9], v[94:95], v[22:23] op_sel:[0,1,0] op_sel_hi:[1,1,1]
	v_pk_mul_f32 v[32:33], v[110:111], v[134:135] op_sel:[1,0] op_sel_hi:[1,1]
	ds_read_b128 v[56:59], v47 offset:1552
	v_pk_fma_f32 v[22:23], v[10:11], v[96:97], v[22:23] op_sel:[0,0,0] op_sel_hi:[1,0,1]
	v_pk_mul_f32 v[34:35], v[112:113], v[134:135] op_sel:[0,0] op_sel_hi:[0,1]
	ds_read_b128 v[68:71], v47 offset:9728
	v_pk_fma_f32 v[22:23], v[12:13], v[96:97], v[22:23] op_sel:[0,1,0] op_sel_hi:[1,1,1]
	v_pk_mul_f32 v[36:37], v[112:113], v[134:135] op_sel:[1,0] op_sel_hi:[1,1]
	ds_read_b128 v[72:75], v47 offset:9744
	v_pk_fma_f32 v[22:23], v[14:15], v[98:99], v[22:23] op_sel:[0,0,0] op_sel_hi:[1,0,1]
	v_pk_mul_f32 v[38:39], v[114:115], v[134:135] op_sel:[0,0] op_sel_hi:[0,1]
	ds_read_b64 v[92:93], v48 offset:1536
	v_pk_fma_f32 v[22:23], v[16:17], v[98:99], v[22:23] op_sel:[0,1,0] op_sel_hi:[1,1,1]
	v_pk_mul_f32 v[40:41], v[114:115], v[134:135] op_sel:[1,0] op_sel_hi:[1,1]
	ds_read_b128 v[84:87], v47 offset:17920
	v_pk_fma_f32 v[22:23], v[18:19], v[100:101], v[22:23] op_sel:[0,0,0] op_sel_hi:[1,0,1]
	v_pk_mul_f32 v[42:43], v[116:117], v[134:135] op_sel:[0,0] op_sel_hi:[0,1]
	ds_read_b128 v[88:91], v47 offset:17936
	v_pk_fma_f32 v[22:23], v[20:21], v[100:101], v[22:23] op_sel:[0,1,0] op_sel_hi:[1,1,1]
	v_pk_mul_f32 v[44:45], v[116:117], v[134:135] op_sel:[1,0] op_sel_hi:[1,1]
	ds_read_b128 v[60:63], v47 offset:5632
	v_pk_fma_f32 v[30:31], v[126:127], v[6:7], v[30:31] op_sel:[0,0,0] op_sel_hi:[0,1,1]
	v_pk_fma_f32 v[32:33], v[126:127], v[8:9], v[32:33] op_sel:[1,0,0] op_sel_hi:[1,1,1]
	ds_read_b128 v[64:67], v47 offset:5648
	v_pk_fma_f32 v[34:35], v[128:129], v[10:11], v[34:35] op_sel:[0,0,0] op_sel_hi:[0,1,1]
	v_pk_fma_f32 v[36:37], v[128:129], v[12:13], v[36:37] op_sel:[1,0,0] op_sel_hi:[1,1,1]
	ds_read_b128 v[76:79], v47 offset:13824
	v_add_f32_dpp v22, v22, v22 quad_perm:[1,0,3,2] row_mask:0xf bank_mask:0xf
	v_add_f32_dpp v23, v23, v23 quad_perm:[1,0,3,2] row_mask:0xf bank_mask:0xf
	ds_read_b128 v[80:83], v47 offset:13840
	v_add_f32_dpp v26, v26, v26 quad_perm:[1,0,3,2] row_mask:0xf bank_mask:0xf
	v_add_f32_dpp v27, v27, v27 quad_perm:[1,0,3,2] row_mask:0xf bank_mask:0xf
	v_pk_fma_f32 v[38:39], v[130:131], v[14:15], v[38:39] op_sel:[0,0,0] op_sel_hi:[0,1,1]
	v_pk_fma_f32 v[40:41], v[130:131], v[16:17], v[40:41] op_sel:[1,0,0] op_sel_hi:[1,1,1]
	v_add_f32_dpp v22, v22, v22 quad_perm:[2,3,0,1] row_mask:0xf bank_mask:0xf
	v_add_f32_dpp v23, v23, v23 quad_perm:[2,3,0,1] row_mask:0xf bank_mask:0xf
	v_add_f32_dpp v26, v26, v26 quad_perm:[2,3,0,1] row_mask:0xf bank_mask:0xf
	v_add_f32_dpp v27, v27, v27 quad_perm:[2,3,0,1] row_mask:0xf bank_mask:0xf
	v_pk_fma_f32 v[42:43], v[132:133], v[18:19], v[42:43] op_sel:[0,0,0] op_sel_hi:[0,1,1]
	v_pk_fma_f32 v[44:45], v[132:133], v[20:21], v[44:45] op_sel:[1,0,0] op_sel_hi:[1,1,1]
	v_add_f32_dpp v22, v22, v22 row_half_mirror row_mask:0xf bank_mask:0xf
	v_add_f32_dpp v23, v23, v23 row_half_mirror row_mask:0xf bank_mask:0xf
	v_add_f32_dpp v26, v26, v26 row_half_mirror row_mask:0xf bank_mask:0xf
	v_add_f32_dpp v27, v27, v27 row_half_mirror row_mask:0xf bank_mask:0xf
	s_waitcnt lgkmcnt(12)
	v_pk_fma_f32 v[6:7], v[102:103], v[22:23], v[30:31] op_sel:[0,0,0] op_sel_hi:[0,1,1] neg_lo:[0,1,0] neg_hi:[0,1,0]
	v_cvt_pk_f16_f32 v46, v26, v27
	v_pk_fma_f32 v[8:9], v[102:103], v[22:23], v[32:33] op_sel:[1,0,0] op_sel_hi:[1,1,1] neg_lo:[0,1,0] neg_hi:[0,1,0]
	v_pk_mul_f32 v[26:27], v[6:7], v[118:119] op_sel:[0,0] op_sel_hi:[1,0]
	v_pk_fma_f32 v[10:11], v[104:105], v[22:23], v[34:35] op_sel:[0,0,0] op_sel_hi:[0,1,1] neg_lo:[0,1,0] neg_hi:[0,1,0]
	v_pk_fma_f32 v[26:27], v[8:9], v[118:119], v[26:27] op_sel:[0,1,0] op_sel_hi:[1,1,1]
	v_pk_fma_f32 v[12:13], v[104:105], v[22:23], v[36:37] op_sel:[1,0,0] op_sel_hi:[1,1,1] neg_lo:[0,1,0] neg_hi:[0,1,0]
	v_pk_fma_f32 v[26:27], v[10:11], v[120:121], v[26:27] op_sel:[0,0,0] op_sel_hi:[1,0,1]
	v_pk_fma_f32 v[14:15], v[106:107], v[22:23], v[38:39] op_sel:[0,0,0] op_sel_hi:[0,1,1] neg_lo:[0,1,0] neg_hi:[0,1,0]
	v_pk_fma_f32 v[26:27], v[12:13], v[120:121], v[26:27] op_sel:[0,1,0] op_sel_hi:[1,1,1]
	v_pk_fma_f32 v[16:17], v[106:107], v[22:23], v[40:41] op_sel:[1,0,0] op_sel_hi:[1,1,1] neg_lo:[0,1,0] neg_hi:[0,1,0]
	v_pk_fma_f32 v[26:27], v[14:15], v[122:123], v[26:27] op_sel:[0,0,0] op_sel_hi:[1,0,1]
	v_pk_fma_f32 v[18:19], v[108:109], v[22:23], v[42:43] op_sel:[0,0,0] op_sel_hi:[0,1,1] neg_lo:[0,1,0] neg_hi:[0,1,0]
	v_pk_fma_f32 v[26:27], v[16:17], v[122:123], v[26:27] op_sel:[0,1,0] op_sel_hi:[1,1,1]
	v_pk_fma_f32 v[20:21], v[108:109], v[22:23], v[44:45] op_sel:[1,0,0] op_sel_hi:[1,1,1] neg_lo:[0,1,0] neg_hi:[0,1,0]
	v_pk_fma_f32 v[26:27], v[18:19], v[124:125], v[26:27] op_sel:[0,0,0] op_sel_hi:[1,0,1]
	ds_write_b32 v49, v46 offset:512
	v_pk_fma_f32 v[26:27], v[20:21], v[124:125], v[26:27] op_sel:[0,1,0] op_sel_hi:[1,1,1]
	s_waitcnt lgkmcnt(5)
	v_pk_mul_f32 v[22:23], v[6:7], v[52:53] op_sel:[0,0] op_sel_hi:[1,0]
	v_pk_mul_f32 v[30:31], v[68:69], v[92:93] op_sel:[0,0] op_sel_hi:[0,1]
	ds_read_b128 v[94:97], v47 offset:1792
	v_pk_fma_f32 v[22:23], v[8:9], v[52:53], v[22:23] op_sel:[0,1,0] op_sel_hi:[1,1,1]
	v_pk_mul_f32 v[32:33], v[68:69], v[92:93] op_sel:[1,0] op_sel_hi:[1,1]
	ds_read_b128 v[98:101], v47 offset:1808
	v_pk_fma_f32 v[22:23], v[10:11], v[54:55], v[22:23] op_sel:[0,0,0] op_sel_hi:[1,0,1]
	v_pk_mul_f32 v[34:35], v[70:71], v[92:93] op_sel:[0,0] op_sel_hi:[0,1]
	ds_read_b128 v[110:113], v47 offset:9984
	v_pk_fma_f32 v[22:23], v[12:13], v[54:55], v[22:23] op_sel:[0,1,0] op_sel_hi:[1,1,1]
	v_pk_mul_f32 v[36:37], v[70:71], v[92:93] op_sel:[1,0] op_sel_hi:[1,1]
	ds_read_b128 v[114:117], v47 offset:10000
	v_pk_fma_f32 v[22:23], v[14:15], v[56:57], v[22:23] op_sel:[0,0,0] op_sel_hi:[1,0,1]
	v_pk_mul_f32 v[38:39], v[72:73], v[92:93] op_sel:[0,0] op_sel_hi:[0,1]
	ds_read_b64 v[134:135], v48 offset:1792
	v_pk_fma_f32 v[22:23], v[16:17], v[56:57], v[22:23] op_sel:[0,1,0] op_sel_hi:[1,1,1]
	v_pk_mul_f32 v[40:41], v[72:73], v[92:93] op_sel:[1,0] op_sel_hi:[1,1]
	ds_read_b128 v[126:129], v47 offset:18176
	v_pk_fma_f32 v[22:23], v[18:19], v[58:59], v[22:23] op_sel:[0,0,0] op_sel_hi:[1,0,1]
	v_pk_mul_f32 v[42:43], v[74:75], v[92:93] op_sel:[0,0] op_sel_hi:[0,1]
	ds_read_b128 v[130:133], v47 offset:18192
	v_pk_fma_f32 v[22:23], v[20:21], v[58:59], v[22:23] op_sel:[0,1,0] op_sel_hi:[1,1,1]
	v_pk_mul_f32 v[44:45], v[74:75], v[92:93] op_sel:[1,0] op_sel_hi:[1,1]
	ds_read_b128 v[102:105], v47 offset:5888
	v_pk_fma_f32 v[30:31], v[84:85], v[6:7], v[30:31] op_sel:[0,0,0] op_sel_hi:[0,1,1]
	v_pk_fma_f32 v[32:33], v[84:85], v[8:9], v[32:33] op_sel:[1,0,0] op_sel_hi:[1,1,1]
	ds_read_b128 v[106:109], v47 offset:5904
	v_pk_fma_f32 v[34:35], v[86:87], v[10:11], v[34:35] op_sel:[0,0,0] op_sel_hi:[0,1,1]
	v_pk_fma_f32 v[36:37], v[86:87], v[12:13], v[36:37] op_sel:[1,0,0] op_sel_hi:[1,1,1]
	ds_read_b128 v[118:121], v47 offset:14080
	v_add_f32_dpp v22, v22, v22 quad_perm:[1,0,3,2] row_mask:0xf bank_mask:0xf
	v_add_f32_dpp v23, v23, v23 quad_perm:[1,0,3,2] row_mask:0xf bank_mask:0xf
	ds_read_b128 v[122:125], v47 offset:14096
	v_add_f32_dpp v26, v26, v26 quad_perm:[1,0,3,2] row_mask:0xf bank_mask:0xf
	v_add_f32_dpp v27, v27, v27 quad_perm:[1,0,3,2] row_mask:0xf bank_mask:0xf
	v_pk_fma_f32 v[38:39], v[88:89], v[14:15], v[38:39] op_sel:[0,0,0] op_sel_hi:[0,1,1]
	v_pk_fma_f32 v[40:41], v[88:89], v[16:17], v[40:41] op_sel:[1,0,0] op_sel_hi:[1,1,1]
	v_add_f32_dpp v22, v22, v22 quad_perm:[2,3,0,1] row_mask:0xf bank_mask:0xf
	v_add_f32_dpp v23, v23, v23 quad_perm:[2,3,0,1] row_mask:0xf bank_mask:0xf
	v_add_f32_dpp v26, v26, v26 quad_perm:[2,3,0,1] row_mask:0xf bank_mask:0xf
	v_add_f32_dpp v27, v27, v27 quad_perm:[2,3,0,1] row_mask:0xf bank_mask:0xf
	v_pk_fma_f32 v[42:43], v[90:91], v[18:19], v[42:43] op_sel:[0,0,0] op_sel_hi:[0,1,1]
	v_pk_fma_f32 v[44:45], v[90:91], v[20:21], v[44:45] op_sel:[1,0,0] op_sel_hi:[1,1,1]
	v_add_f32_dpp v22, v22, v22 row_half_mirror row_mask:0xf bank_mask:0xf
	v_add_f32_dpp v23, v23, v23 row_half_mirror row_mask:0xf bank_mask:0xf
	v_add_f32_dpp v26, v26, v26 row_half_mirror row_mask:0xf bank_mask:0xf
	v_add_f32_dpp v27, v27, v27 row_half_mirror row_mask:0xf bank_mask:0xf
	s_waitcnt lgkmcnt(12)
	v_pk_fma_f32 v[6:7], v[60:61], v[22:23], v[30:31] op_sel:[0,0,0] op_sel_hi:[0,1,1] neg_lo:[0,1,0] neg_hi:[0,1,0]
	v_cvt_pk_f16_f32 v46, v26, v27
	v_pk_fma_f32 v[8:9], v[60:61], v[22:23], v[32:33] op_sel:[1,0,0] op_sel_hi:[1,1,1] neg_lo:[0,1,0] neg_hi:[0,1,0]
	v_pk_mul_f32 v[26:27], v[6:7], v[76:77] op_sel:[0,0] op_sel_hi:[1,0]
	v_pk_fma_f32 v[10:11], v[62:63], v[22:23], v[34:35] op_sel:[0,0,0] op_sel_hi:[0,1,1] neg_lo:[0,1,0] neg_hi:[0,1,0]
	v_pk_fma_f32 v[26:27], v[8:9], v[76:77], v[26:27] op_sel:[0,1,0] op_sel_hi:[1,1,1]
	v_pk_fma_f32 v[12:13], v[62:63], v[22:23], v[36:37] op_sel:[1,0,0] op_sel_hi:[1,1,1] neg_lo:[0,1,0] neg_hi:[0,1,0]
	v_pk_fma_f32 v[26:27], v[10:11], v[78:79], v[26:27] op_sel:[0,0,0] op_sel_hi:[1,0,1]
	v_pk_fma_f32 v[14:15], v[64:65], v[22:23], v[38:39] op_sel:[0,0,0] op_sel_hi:[0,1,1] neg_lo:[0,1,0] neg_hi:[0,1,0]
	v_pk_fma_f32 v[26:27], v[12:13], v[78:79], v[26:27] op_sel:[0,1,0] op_sel_hi:[1,1,1]
	v_pk_fma_f32 v[16:17], v[64:65], v[22:23], v[40:41] op_sel:[1,0,0] op_sel_hi:[1,1,1] neg_lo:[0,1,0] neg_hi:[0,1,0]
	v_pk_fma_f32 v[26:27], v[14:15], v[80:81], v[26:27] op_sel:[0,0,0] op_sel_hi:[1,0,1]
	v_pk_fma_f32 v[18:19], v[66:67], v[22:23], v[42:43] op_sel:[0,0,0] op_sel_hi:[0,1,1] neg_lo:[0,1,0] neg_hi:[0,1,0]
	v_pk_fma_f32 v[26:27], v[16:17], v[80:81], v[26:27] op_sel:[0,1,0] op_sel_hi:[1,1,1]
	v_pk_fma_f32 v[20:21], v[66:67], v[22:23], v[44:45] op_sel:[1,0,0] op_sel_hi:[1,1,1] neg_lo:[0,1,0] neg_hi:[0,1,0]
	v_pk_fma_f32 v[26:27], v[18:19], v[82:83], v[26:27] op_sel:[0,0,0] op_sel_hi:[1,0,1]
	ds_write_b32 v49, v46 offset:640
	v_pk_fma_f32 v[26:27], v[20:21], v[82:83], v[26:27] op_sel:[0,1,0] op_sel_hi:[1,1,1]
	s_waitcnt lgkmcnt(5)
	v_pk_mul_f32 v[22:23], v[6:7], v[94:95] op_sel:[0,0] op_sel_hi:[1,0]
	v_pk_mul_f32 v[30:31], v[110:111], v[134:135] op_sel:[0,0] op_sel_hi:[0,1]
	ds_read_b128 v[52:55], v47 offset:2048
	v_pk_fma_f32 v[22:23], v[8:9], v[94:95], v[22:23] op_sel:[0,1,0] op_sel_hi:[1,1,1]
	v_pk_mul_f32 v[32:33], v[110:111], v[134:135] op_sel:[1,0] op_sel_hi:[1,1]
	ds_read_b128 v[56:59], v47 offset:2064
	v_pk_fma_f32 v[22:23], v[10:11], v[96:97], v[22:23] op_sel:[0,0,0] op_sel_hi:[1,0,1]
	v_pk_mul_f32 v[34:35], v[112:113], v[134:135] op_sel:[0,0] op_sel_hi:[0,1]
	ds_read_b128 v[68:71], v47 offset:10240
	v_pk_fma_f32 v[22:23], v[12:13], v[96:97], v[22:23] op_sel:[0,1,0] op_sel_hi:[1,1,1]
	v_pk_mul_f32 v[36:37], v[112:113], v[134:135] op_sel:[1,0] op_sel_hi:[1,1]
	ds_read_b128 v[72:75], v47 offset:10256
	v_pk_fma_f32 v[22:23], v[14:15], v[98:99], v[22:23] op_sel:[0,0,0] op_sel_hi:[1,0,1]
	v_pk_mul_f32 v[38:39], v[114:115], v[134:135] op_sel:[0,0] op_sel_hi:[0,1]
	ds_read_b64 v[92:93], v48 offset:2048
	v_pk_fma_f32 v[22:23], v[16:17], v[98:99], v[22:23] op_sel:[0,1,0] op_sel_hi:[1,1,1]
	v_pk_mul_f32 v[40:41], v[114:115], v[134:135] op_sel:[1,0] op_sel_hi:[1,1]
	ds_read_b128 v[84:87], v47 offset:18432
	v_pk_fma_f32 v[22:23], v[18:19], v[100:101], v[22:23] op_sel:[0,0,0] op_sel_hi:[1,0,1]
	v_pk_mul_f32 v[42:43], v[116:117], v[134:135] op_sel:[0,0] op_sel_hi:[0,1]
	ds_read_b128 v[88:91], v47 offset:18448
	v_pk_fma_f32 v[22:23], v[20:21], v[100:101], v[22:23] op_sel:[0,1,0] op_sel_hi:[1,1,1]
	v_pk_mul_f32 v[44:45], v[116:117], v[134:135] op_sel:[1,0] op_sel_hi:[1,1]
	ds_read_b128 v[60:63], v47 offset:6144
	v_pk_fma_f32 v[30:31], v[126:127], v[6:7], v[30:31] op_sel:[0,0,0] op_sel_hi:[0,1,1]
	v_pk_fma_f32 v[32:33], v[126:127], v[8:9], v[32:33] op_sel:[1,0,0] op_sel_hi:[1,1,1]
	ds_read_b128 v[64:67], v47 offset:6160
	v_pk_fma_f32 v[34:35], v[128:129], v[10:11], v[34:35] op_sel:[0,0,0] op_sel_hi:[0,1,1]
	v_pk_fma_f32 v[36:37], v[128:129], v[12:13], v[36:37] op_sel:[1,0,0] op_sel_hi:[1,1,1]
	ds_read_b128 v[76:79], v47 offset:14336
	v_add_f32_dpp v22, v22, v22 quad_perm:[1,0,3,2] row_mask:0xf bank_mask:0xf
	v_add_f32_dpp v23, v23, v23 quad_perm:[1,0,3,2] row_mask:0xf bank_mask:0xf
	ds_read_b128 v[80:83], v47 offset:14352
	v_add_f32_dpp v26, v26, v26 quad_perm:[1,0,3,2] row_mask:0xf bank_mask:0xf
	v_add_f32_dpp v27, v27, v27 quad_perm:[1,0,3,2] row_mask:0xf bank_mask:0xf
	v_pk_fma_f32 v[38:39], v[130:131], v[14:15], v[38:39] op_sel:[0,0,0] op_sel_hi:[0,1,1]
	v_pk_fma_f32 v[40:41], v[130:131], v[16:17], v[40:41] op_sel:[1,0,0] op_sel_hi:[1,1,1]
	v_add_f32_dpp v22, v22, v22 quad_perm:[2,3,0,1] row_mask:0xf bank_mask:0xf
	v_add_f32_dpp v23, v23, v23 quad_perm:[2,3,0,1] row_mask:0xf bank_mask:0xf
	v_add_f32_dpp v26, v26, v26 quad_perm:[2,3,0,1] row_mask:0xf bank_mask:0xf
	v_add_f32_dpp v27, v27, v27 quad_perm:[2,3,0,1] row_mask:0xf bank_mask:0xf
	v_pk_fma_f32 v[42:43], v[132:133], v[18:19], v[42:43] op_sel:[0,0,0] op_sel_hi:[0,1,1]
	v_pk_fma_f32 v[44:45], v[132:133], v[20:21], v[44:45] op_sel:[1,0,0] op_sel_hi:[1,1,1]
	v_add_f32_dpp v22, v22, v22 row_half_mirror row_mask:0xf bank_mask:0xf
	v_add_f32_dpp v23, v23, v23 row_half_mirror row_mask:0xf bank_mask:0xf
	v_add_f32_dpp v26, v26, v26 row_half_mirror row_mask:0xf bank_mask:0xf
	v_add_f32_dpp v27, v27, v27 row_half_mirror row_mask:0xf bank_mask:0xf
	s_waitcnt lgkmcnt(12)
	v_pk_fma_f32 v[6:7], v[102:103], v[22:23], v[30:31] op_sel:[0,0,0] op_sel_hi:[0,1,1] neg_lo:[0,1,0] neg_hi:[0,1,0]
	v_cvt_pk_f16_f32 v46, v26, v27
	v_pk_fma_f32 v[8:9], v[102:103], v[22:23], v[32:33] op_sel:[1,0,0] op_sel_hi:[1,1,1] neg_lo:[0,1,0] neg_hi:[0,1,0]
	v_pk_mul_f32 v[26:27], v[6:7], v[118:119] op_sel:[0,0] op_sel_hi:[1,0]
	v_pk_fma_f32 v[10:11], v[104:105], v[22:23], v[34:35] op_sel:[0,0,0] op_sel_hi:[0,1,1] neg_lo:[0,1,0] neg_hi:[0,1,0]
	v_pk_fma_f32 v[26:27], v[8:9], v[118:119], v[26:27] op_sel:[0,1,0] op_sel_hi:[1,1,1]
	v_pk_fma_f32 v[12:13], v[104:105], v[22:23], v[36:37] op_sel:[1,0,0] op_sel_hi:[1,1,1] neg_lo:[0,1,0] neg_hi:[0,1,0]
	v_pk_fma_f32 v[26:27], v[10:11], v[120:121], v[26:27] op_sel:[0,0,0] op_sel_hi:[1,0,1]
	v_pk_fma_f32 v[14:15], v[106:107], v[22:23], v[38:39] op_sel:[0,0,0] op_sel_hi:[0,1,1] neg_lo:[0,1,0] neg_hi:[0,1,0]
	v_pk_fma_f32 v[26:27], v[12:13], v[120:121], v[26:27] op_sel:[0,1,0] op_sel_hi:[1,1,1]
	v_pk_fma_f32 v[16:17], v[106:107], v[22:23], v[40:41] op_sel:[1,0,0] op_sel_hi:[1,1,1] neg_lo:[0,1,0] neg_hi:[0,1,0]
	v_pk_fma_f32 v[26:27], v[14:15], v[122:123], v[26:27] op_sel:[0,0,0] op_sel_hi:[1,0,1]
	v_pk_fma_f32 v[18:19], v[108:109], v[22:23], v[42:43] op_sel:[0,0,0] op_sel_hi:[0,1,1] neg_lo:[0,1,0] neg_hi:[0,1,0]
	v_pk_fma_f32 v[26:27], v[16:17], v[122:123], v[26:27] op_sel:[0,1,0] op_sel_hi:[1,1,1]
	v_pk_fma_f32 v[20:21], v[108:109], v[22:23], v[44:45] op_sel:[1,0,0] op_sel_hi:[1,1,1] neg_lo:[0,1,0] neg_hi:[0,1,0]
	v_pk_fma_f32 v[26:27], v[18:19], v[124:125], v[26:27] op_sel:[0,0,0] op_sel_hi:[1,0,1]
	ds_write_b32 v49, v46 offset:768
	v_pk_fma_f32 v[26:27], v[20:21], v[124:125], v[26:27] op_sel:[0,1,0] op_sel_hi:[1,1,1]
	s_waitcnt lgkmcnt(5)
	v_pk_mul_f32 v[22:23], v[6:7], v[52:53] op_sel:[0,0] op_sel_hi:[1,0]
	v_pk_mul_f32 v[30:31], v[68:69], v[92:93] op_sel:[0,0] op_sel_hi:[0,1]
	ds_read_b128 v[94:97], v47 offset:2304
	v_pk_fma_f32 v[22:23], v[8:9], v[52:53], v[22:23] op_sel:[0,1,0] op_sel_hi:[1,1,1]
	v_pk_mul_f32 v[32:33], v[68:69], v[92:93] op_sel:[1,0] op_sel_hi:[1,1]
	ds_read_b128 v[98:101], v47 offset:2320
	v_pk_fma_f32 v[22:23], v[10:11], v[54:55], v[22:23] op_sel:[0,0,0] op_sel_hi:[1,0,1]
	v_pk_mul_f32 v[34:35], v[70:71], v[92:93] op_sel:[0,0] op_sel_hi:[0,1]
	ds_read_b128 v[110:113], v47 offset:10496
	v_pk_fma_f32 v[22:23], v[12:13], v[54:55], v[22:23] op_sel:[0,1,0] op_sel_hi:[1,1,1]
	v_pk_mul_f32 v[36:37], v[70:71], v[92:93] op_sel:[1,0] op_sel_hi:[1,1]
	ds_read_b128 v[114:117], v47 offset:10512
	v_pk_fma_f32 v[22:23], v[14:15], v[56:57], v[22:23] op_sel:[0,0,0] op_sel_hi:[1,0,1]
	v_pk_mul_f32 v[38:39], v[72:73], v[92:93] op_sel:[0,0] op_sel_hi:[0,1]
	ds_read_b64 v[134:135], v48 offset:2304
	v_pk_fma_f32 v[22:23], v[16:17], v[56:57], v[22:23] op_sel:[0,1,0] op_sel_hi:[1,1,1]
	v_pk_mul_f32 v[40:41], v[72:73], v[92:93] op_sel:[1,0] op_sel_hi:[1,1]
	ds_read_b128 v[126:129], v47 offset:18688
	v_pk_fma_f32 v[22:23], v[18:19], v[58:59], v[22:23] op_sel:[0,0,0] op_sel_hi:[1,0,1]
	v_pk_mul_f32 v[42:43], v[74:75], v[92:93] op_sel:[0,0] op_sel_hi:[0,1]
	ds_read_b128 v[130:133], v47 offset:18704
	v_pk_fma_f32 v[22:23], v[20:21], v[58:59], v[22:23] op_sel:[0,1,0] op_sel_hi:[1,1,1]
	v_pk_mul_f32 v[44:45], v[74:75], v[92:93] op_sel:[1,0] op_sel_hi:[1,1]
	ds_read_b128 v[102:105], v47 offset:6400
	v_pk_fma_f32 v[30:31], v[84:85], v[6:7], v[30:31] op_sel:[0,0,0] op_sel_hi:[0,1,1]
	v_pk_fma_f32 v[32:33], v[84:85], v[8:9], v[32:33] op_sel:[1,0,0] op_sel_hi:[1,1,1]
	ds_read_b128 v[106:109], v47 offset:6416
	v_pk_fma_f32 v[34:35], v[86:87], v[10:11], v[34:35] op_sel:[0,0,0] op_sel_hi:[0,1,1]
	v_pk_fma_f32 v[36:37], v[86:87], v[12:13], v[36:37] op_sel:[1,0,0] op_sel_hi:[1,1,1]
	ds_read_b128 v[118:121], v47 offset:14592
	v_add_f32_dpp v22, v22, v22 quad_perm:[1,0,3,2] row_mask:0xf bank_mask:0xf
	v_add_f32_dpp v23, v23, v23 quad_perm:[1,0,3,2] row_mask:0xf bank_mask:0xf
	ds_read_b128 v[122:125], v47 offset:14608
	v_add_f32_dpp v26, v26, v26 quad_perm:[1,0,3,2] row_mask:0xf bank_mask:0xf
	v_add_f32_dpp v27, v27, v27 quad_perm:[1,0,3,2] row_mask:0xf bank_mask:0xf
	v_pk_fma_f32 v[38:39], v[88:89], v[14:15], v[38:39] op_sel:[0,0,0] op_sel_hi:[0,1,1]
	v_pk_fma_f32 v[40:41], v[88:89], v[16:17], v[40:41] op_sel:[1,0,0] op_sel_hi:[1,1,1]
	v_add_f32_dpp v22, v22, v22 quad_perm:[2,3,0,1] row_mask:0xf bank_mask:0xf
	v_add_f32_dpp v23, v23, v23 quad_perm:[2,3,0,1] row_mask:0xf bank_mask:0xf
	v_add_f32_dpp v26, v26, v26 quad_perm:[2,3,0,1] row_mask:0xf bank_mask:0xf
	v_add_f32_dpp v27, v27, v27 quad_perm:[2,3,0,1] row_mask:0xf bank_mask:0xf
	v_pk_fma_f32 v[42:43], v[90:91], v[18:19], v[42:43] op_sel:[0,0,0] op_sel_hi:[0,1,1]
	v_pk_fma_f32 v[44:45], v[90:91], v[20:21], v[44:45] op_sel:[1,0,0] op_sel_hi:[1,1,1]
	v_add_f32_dpp v22, v22, v22 row_half_mirror row_mask:0xf bank_mask:0xf
	v_add_f32_dpp v23, v23, v23 row_half_mirror row_mask:0xf bank_mask:0xf
	v_add_f32_dpp v26, v26, v26 row_half_mirror row_mask:0xf bank_mask:0xf
	v_add_f32_dpp v27, v27, v27 row_half_mirror row_mask:0xf bank_mask:0xf
	s_waitcnt lgkmcnt(12)
	v_pk_fma_f32 v[6:7], v[60:61], v[22:23], v[30:31] op_sel:[0,0,0] op_sel_hi:[0,1,1] neg_lo:[0,1,0] neg_hi:[0,1,0]
	v_cvt_pk_f16_f32 v46, v26, v27
	v_pk_fma_f32 v[8:9], v[60:61], v[22:23], v[32:33] op_sel:[1,0,0] op_sel_hi:[1,1,1] neg_lo:[0,1,0] neg_hi:[0,1,0]
	v_pk_mul_f32 v[26:27], v[6:7], v[76:77] op_sel:[0,0] op_sel_hi:[1,0]
	v_pk_fma_f32 v[10:11], v[62:63], v[22:23], v[34:35] op_sel:[0,0,0] op_sel_hi:[0,1,1] neg_lo:[0,1,0] neg_hi:[0,1,0]
	v_pk_fma_f32 v[26:27], v[8:9], v[76:77], v[26:27] op_sel:[0,1,0] op_sel_hi:[1,1,1]
	v_pk_fma_f32 v[12:13], v[62:63], v[22:23], v[36:37] op_sel:[1,0,0] op_sel_hi:[1,1,1] neg_lo:[0,1,0] neg_hi:[0,1,0]
	v_pk_fma_f32 v[26:27], v[10:11], v[78:79], v[26:27] op_sel:[0,0,0] op_sel_hi:[1,0,1]
	v_pk_fma_f32 v[14:15], v[64:65], v[22:23], v[38:39] op_sel:[0,0,0] op_sel_hi:[0,1,1] neg_lo:[0,1,0] neg_hi:[0,1,0]
	v_pk_fma_f32 v[26:27], v[12:13], v[78:79], v[26:27] op_sel:[0,1,0] op_sel_hi:[1,1,1]
	v_pk_fma_f32 v[16:17], v[64:65], v[22:23], v[40:41] op_sel:[1,0,0] op_sel_hi:[1,1,1] neg_lo:[0,1,0] neg_hi:[0,1,0]
	v_pk_fma_f32 v[26:27], v[14:15], v[80:81], v[26:27] op_sel:[0,0,0] op_sel_hi:[1,0,1]
	v_pk_fma_f32 v[18:19], v[66:67], v[22:23], v[42:43] op_sel:[0,0,0] op_sel_hi:[0,1,1] neg_lo:[0,1,0] neg_hi:[0,1,0]
	v_pk_fma_f32 v[26:27], v[16:17], v[80:81], v[26:27] op_sel:[0,1,0] op_sel_hi:[1,1,1]
	v_pk_fma_f32 v[20:21], v[66:67], v[22:23], v[44:45] op_sel:[1,0,0] op_sel_hi:[1,1,1] neg_lo:[0,1,0] neg_hi:[0,1,0]
	v_pk_fma_f32 v[26:27], v[18:19], v[82:83], v[26:27] op_sel:[0,0,0] op_sel_hi:[1,0,1]
	ds_write_b32 v49, v46 offset:896
	v_pk_fma_f32 v[26:27], v[20:21], v[82:83], v[26:27] op_sel:[0,1,0] op_sel_hi:[1,1,1]
	s_waitcnt lgkmcnt(5)
	v_pk_mul_f32 v[22:23], v[6:7], v[94:95] op_sel:[0,0] op_sel_hi:[1,0]
	v_pk_mul_f32 v[30:31], v[110:111], v[134:135] op_sel:[0,0] op_sel_hi:[0,1]
	ds_read_b128 v[52:55], v47 offset:2560
	v_pk_fma_f32 v[22:23], v[8:9], v[94:95], v[22:23] op_sel:[0,1,0] op_sel_hi:[1,1,1]
	v_pk_mul_f32 v[32:33], v[110:111], v[134:135] op_sel:[1,0] op_sel_hi:[1,1]
	ds_read_b128 v[56:59], v47 offset:2576
	v_pk_fma_f32 v[22:23], v[10:11], v[96:97], v[22:23] op_sel:[0,0,0] op_sel_hi:[1,0,1]
	v_pk_mul_f32 v[34:35], v[112:113], v[134:135] op_sel:[0,0] op_sel_hi:[0,1]
	ds_read_b128 v[68:71], v47 offset:10752
	v_pk_fma_f32 v[22:23], v[12:13], v[96:97], v[22:23] op_sel:[0,1,0] op_sel_hi:[1,1,1]
	v_pk_mul_f32 v[36:37], v[112:113], v[134:135] op_sel:[1,0] op_sel_hi:[1,1]
	ds_read_b128 v[72:75], v47 offset:10768
	v_pk_fma_f32 v[22:23], v[14:15], v[98:99], v[22:23] op_sel:[0,0,0] op_sel_hi:[1,0,1]
	v_pk_mul_f32 v[38:39], v[114:115], v[134:135] op_sel:[0,0] op_sel_hi:[0,1]
	ds_read_b64 v[92:93], v48 offset:2560
	v_pk_fma_f32 v[22:23], v[16:17], v[98:99], v[22:23] op_sel:[0,1,0] op_sel_hi:[1,1,1]
	v_pk_mul_f32 v[40:41], v[114:115], v[134:135] op_sel:[1,0] op_sel_hi:[1,1]
	ds_read_b128 v[84:87], v47 offset:18944
	v_pk_fma_f32 v[22:23], v[18:19], v[100:101], v[22:23] op_sel:[0,0,0] op_sel_hi:[1,0,1]
	v_pk_mul_f32 v[42:43], v[116:117], v[134:135] op_sel:[0,0] op_sel_hi:[0,1]
	ds_read_b128 v[88:91], v47 offset:18960
	v_pk_fma_f32 v[22:23], v[20:21], v[100:101], v[22:23] op_sel:[0,1,0] op_sel_hi:[1,1,1]
	v_pk_mul_f32 v[44:45], v[116:117], v[134:135] op_sel:[1,0] op_sel_hi:[1,1]
	ds_read_b128 v[60:63], v47 offset:6656
	v_pk_fma_f32 v[30:31], v[126:127], v[6:7], v[30:31] op_sel:[0,0,0] op_sel_hi:[0,1,1]
	v_pk_fma_f32 v[32:33], v[126:127], v[8:9], v[32:33] op_sel:[1,0,0] op_sel_hi:[1,1,1]
	ds_read_b128 v[64:67], v47 offset:6672
	v_pk_fma_f32 v[34:35], v[128:129], v[10:11], v[34:35] op_sel:[0,0,0] op_sel_hi:[0,1,1]
	v_pk_fma_f32 v[36:37], v[128:129], v[12:13], v[36:37] op_sel:[1,0,0] op_sel_hi:[1,1,1]
	ds_read_b128 v[76:79], v47 offset:14848
	v_add_f32_dpp v22, v22, v22 quad_perm:[1,0,3,2] row_mask:0xf bank_mask:0xf
	v_add_f32_dpp v23, v23, v23 quad_perm:[1,0,3,2] row_mask:0xf bank_mask:0xf
	ds_read_b128 v[80:83], v47 offset:14864
	v_add_f32_dpp v26, v26, v26 quad_perm:[1,0,3,2] row_mask:0xf bank_mask:0xf
	v_add_f32_dpp v27, v27, v27 quad_perm:[1,0,3,2] row_mask:0xf bank_mask:0xf
	v_pk_fma_f32 v[38:39], v[130:131], v[14:15], v[38:39] op_sel:[0,0,0] op_sel_hi:[0,1,1]
	v_pk_fma_f32 v[40:41], v[130:131], v[16:17], v[40:41] op_sel:[1,0,0] op_sel_hi:[1,1,1]
	v_add_f32_dpp v22, v22, v22 quad_perm:[2,3,0,1] row_mask:0xf bank_mask:0xf
	v_add_f32_dpp v23, v23, v23 quad_perm:[2,3,0,1] row_mask:0xf bank_mask:0xf
	v_add_f32_dpp v26, v26, v26 quad_perm:[2,3,0,1] row_mask:0xf bank_mask:0xf
	v_add_f32_dpp v27, v27, v27 quad_perm:[2,3,0,1] row_mask:0xf bank_mask:0xf
	v_pk_fma_f32 v[42:43], v[132:133], v[18:19], v[42:43] op_sel:[0,0,0] op_sel_hi:[0,1,1]
	v_pk_fma_f32 v[44:45], v[132:133], v[20:21], v[44:45] op_sel:[1,0,0] op_sel_hi:[1,1,1]
	v_add_f32_dpp v22, v22, v22 row_half_mirror row_mask:0xf bank_mask:0xf
	v_add_f32_dpp v23, v23, v23 row_half_mirror row_mask:0xf bank_mask:0xf
	v_add_f32_dpp v26, v26, v26 row_half_mirror row_mask:0xf bank_mask:0xf
	v_add_f32_dpp v27, v27, v27 row_half_mirror row_mask:0xf bank_mask:0xf
	s_waitcnt lgkmcnt(12)
	v_pk_fma_f32 v[6:7], v[102:103], v[22:23], v[30:31] op_sel:[0,0,0] op_sel_hi:[0,1,1] neg_lo:[0,1,0] neg_hi:[0,1,0]
	v_cvt_pk_f16_f32 v46, v26, v27
	v_pk_fma_f32 v[8:9], v[102:103], v[22:23], v[32:33] op_sel:[1,0,0] op_sel_hi:[1,1,1] neg_lo:[0,1,0] neg_hi:[0,1,0]
	v_pk_mul_f32 v[26:27], v[6:7], v[118:119] op_sel:[0,0] op_sel_hi:[1,0]
	v_pk_fma_f32 v[10:11], v[104:105], v[22:23], v[34:35] op_sel:[0,0,0] op_sel_hi:[0,1,1] neg_lo:[0,1,0] neg_hi:[0,1,0]
	v_pk_fma_f32 v[26:27], v[8:9], v[118:119], v[26:27] op_sel:[0,1,0] op_sel_hi:[1,1,1]
	v_pk_fma_f32 v[12:13], v[104:105], v[22:23], v[36:37] op_sel:[1,0,0] op_sel_hi:[1,1,1] neg_lo:[0,1,0] neg_hi:[0,1,0]
	v_pk_fma_f32 v[26:27], v[10:11], v[120:121], v[26:27] op_sel:[0,0,0] op_sel_hi:[1,0,1]
	v_pk_fma_f32 v[14:15], v[106:107], v[22:23], v[38:39] op_sel:[0,0,0] op_sel_hi:[0,1,1] neg_lo:[0,1,0] neg_hi:[0,1,0]
	v_pk_fma_f32 v[26:27], v[12:13], v[120:121], v[26:27] op_sel:[0,1,0] op_sel_hi:[1,1,1]
	v_pk_fma_f32 v[16:17], v[106:107], v[22:23], v[40:41] op_sel:[1,0,0] op_sel_hi:[1,1,1] neg_lo:[0,1,0] neg_hi:[0,1,0]
	v_pk_fma_f32 v[26:27], v[14:15], v[122:123], v[26:27] op_sel:[0,0,0] op_sel_hi:[1,0,1]
	v_pk_fma_f32 v[18:19], v[108:109], v[22:23], v[42:43] op_sel:[0,0,0] op_sel_hi:[0,1,1] neg_lo:[0,1,0] neg_hi:[0,1,0]
	v_pk_fma_f32 v[26:27], v[16:17], v[122:123], v[26:27] op_sel:[0,1,0] op_sel_hi:[1,1,1]
	v_pk_fma_f32 v[20:21], v[108:109], v[22:23], v[44:45] op_sel:[1,0,0] op_sel_hi:[1,1,1] neg_lo:[0,1,0] neg_hi:[0,1,0]
	v_pk_fma_f32 v[26:27], v[18:19], v[124:125], v[26:27] op_sel:[0,0,0] op_sel_hi:[1,0,1]
	ds_write_b32 v49, v46 offset:1024
	v_pk_fma_f32 v[26:27], v[20:21], v[124:125], v[26:27] op_sel:[0,1,0] op_sel_hi:[1,1,1]
	s_waitcnt lgkmcnt(5)
	v_pk_mul_f32 v[22:23], v[6:7], v[52:53] op_sel:[0,0] op_sel_hi:[1,0]
	v_pk_mul_f32 v[30:31], v[68:69], v[92:93] op_sel:[0,0] op_sel_hi:[0,1]
	ds_read_b128 v[94:97], v47 offset:2816
	v_pk_fma_f32 v[22:23], v[8:9], v[52:53], v[22:23] op_sel:[0,1,0] op_sel_hi:[1,1,1]
	v_pk_mul_f32 v[32:33], v[68:69], v[92:93] op_sel:[1,0] op_sel_hi:[1,1]
	ds_read_b128 v[98:101], v47 offset:2832
	v_pk_fma_f32 v[22:23], v[10:11], v[54:55], v[22:23] op_sel:[0,0,0] op_sel_hi:[1,0,1]
	v_pk_mul_f32 v[34:35], v[70:71], v[92:93] op_sel:[0,0] op_sel_hi:[0,1]
	ds_read_b128 v[110:113], v47 offset:11008
	v_pk_fma_f32 v[22:23], v[12:13], v[54:55], v[22:23] op_sel:[0,1,0] op_sel_hi:[1,1,1]
	v_pk_mul_f32 v[36:37], v[70:71], v[92:93] op_sel:[1,0] op_sel_hi:[1,1]
	ds_read_b128 v[114:117], v47 offset:11024
	v_pk_fma_f32 v[22:23], v[14:15], v[56:57], v[22:23] op_sel:[0,0,0] op_sel_hi:[1,0,1]
	v_pk_mul_f32 v[38:39], v[72:73], v[92:93] op_sel:[0,0] op_sel_hi:[0,1]
	ds_read_b64 v[134:135], v48 offset:2816
	v_pk_fma_f32 v[22:23], v[16:17], v[56:57], v[22:23] op_sel:[0,1,0] op_sel_hi:[1,1,1]
	v_pk_mul_f32 v[40:41], v[72:73], v[92:93] op_sel:[1,0] op_sel_hi:[1,1]
	ds_read_b128 v[126:129], v47 offset:19200
	v_pk_fma_f32 v[22:23], v[18:19], v[58:59], v[22:23] op_sel:[0,0,0] op_sel_hi:[1,0,1]
	v_pk_mul_f32 v[42:43], v[74:75], v[92:93] op_sel:[0,0] op_sel_hi:[0,1]
	ds_read_b128 v[130:133], v47 offset:19216
	v_pk_fma_f32 v[22:23], v[20:21], v[58:59], v[22:23] op_sel:[0,1,0] op_sel_hi:[1,1,1]
	v_pk_mul_f32 v[44:45], v[74:75], v[92:93] op_sel:[1,0] op_sel_hi:[1,1]
	ds_read_b128 v[102:105], v47 offset:6912
	v_pk_fma_f32 v[30:31], v[84:85], v[6:7], v[30:31] op_sel:[0,0,0] op_sel_hi:[0,1,1]
	v_pk_fma_f32 v[32:33], v[84:85], v[8:9], v[32:33] op_sel:[1,0,0] op_sel_hi:[1,1,1]
	ds_read_b128 v[106:109], v47 offset:6928
	v_pk_fma_f32 v[34:35], v[86:87], v[10:11], v[34:35] op_sel:[0,0,0] op_sel_hi:[0,1,1]
	v_pk_fma_f32 v[36:37], v[86:87], v[12:13], v[36:37] op_sel:[1,0,0] op_sel_hi:[1,1,1]
	ds_read_b128 v[118:121], v47 offset:15104
	v_add_f32_dpp v22, v22, v22 quad_perm:[1,0,3,2] row_mask:0xf bank_mask:0xf
	v_add_f32_dpp v23, v23, v23 quad_perm:[1,0,3,2] row_mask:0xf bank_mask:0xf
	ds_read_b128 v[122:125], v47 offset:15120
	v_add_f32_dpp v26, v26, v26 quad_perm:[1,0,3,2] row_mask:0xf bank_mask:0xf
	v_add_f32_dpp v27, v27, v27 quad_perm:[1,0,3,2] row_mask:0xf bank_mask:0xf
	v_pk_fma_f32 v[38:39], v[88:89], v[14:15], v[38:39] op_sel:[0,0,0] op_sel_hi:[0,1,1]
	v_pk_fma_f32 v[40:41], v[88:89], v[16:17], v[40:41] op_sel:[1,0,0] op_sel_hi:[1,1,1]
	v_add_f32_dpp v22, v22, v22 quad_perm:[2,3,0,1] row_mask:0xf bank_mask:0xf
	v_add_f32_dpp v23, v23, v23 quad_perm:[2,3,0,1] row_mask:0xf bank_mask:0xf
	v_add_f32_dpp v26, v26, v26 quad_perm:[2,3,0,1] row_mask:0xf bank_mask:0xf
	v_add_f32_dpp v27, v27, v27 quad_perm:[2,3,0,1] row_mask:0xf bank_mask:0xf
	v_pk_fma_f32 v[42:43], v[90:91], v[18:19], v[42:43] op_sel:[0,0,0] op_sel_hi:[0,1,1]
	v_pk_fma_f32 v[44:45], v[90:91], v[20:21], v[44:45] op_sel:[1,0,0] op_sel_hi:[1,1,1]
	v_add_f32_dpp v22, v22, v22 row_half_mirror row_mask:0xf bank_mask:0xf
	v_add_f32_dpp v23, v23, v23 row_half_mirror row_mask:0xf bank_mask:0xf
	v_add_f32_dpp v26, v26, v26 row_half_mirror row_mask:0xf bank_mask:0xf
	v_add_f32_dpp v27, v27, v27 row_half_mirror row_mask:0xf bank_mask:0xf
	s_waitcnt lgkmcnt(12)
	v_pk_fma_f32 v[6:7], v[60:61], v[22:23], v[30:31] op_sel:[0,0,0] op_sel_hi:[0,1,1] neg_lo:[0,1,0] neg_hi:[0,1,0]
	v_cvt_pk_f16_f32 v46, v26, v27
	v_pk_fma_f32 v[8:9], v[60:61], v[22:23], v[32:33] op_sel:[1,0,0] op_sel_hi:[1,1,1] neg_lo:[0,1,0] neg_hi:[0,1,0]
	v_pk_mul_f32 v[26:27], v[6:7], v[76:77] op_sel:[0,0] op_sel_hi:[1,0]
	v_pk_fma_f32 v[10:11], v[62:63], v[22:23], v[34:35] op_sel:[0,0,0] op_sel_hi:[0,1,1] neg_lo:[0,1,0] neg_hi:[0,1,0]
	v_pk_fma_f32 v[26:27], v[8:9], v[76:77], v[26:27] op_sel:[0,1,0] op_sel_hi:[1,1,1]
	v_pk_fma_f32 v[12:13], v[62:63], v[22:23], v[36:37] op_sel:[1,0,0] op_sel_hi:[1,1,1] neg_lo:[0,1,0] neg_hi:[0,1,0]
	v_pk_fma_f32 v[26:27], v[10:11], v[78:79], v[26:27] op_sel:[0,0,0] op_sel_hi:[1,0,1]
	v_pk_fma_f32 v[14:15], v[64:65], v[22:23], v[38:39] op_sel:[0,0,0] op_sel_hi:[0,1,1] neg_lo:[0,1,0] neg_hi:[0,1,0]
	v_pk_fma_f32 v[26:27], v[12:13], v[78:79], v[26:27] op_sel:[0,1,0] op_sel_hi:[1,1,1]
	v_pk_fma_f32 v[16:17], v[64:65], v[22:23], v[40:41] op_sel:[1,0,0] op_sel_hi:[1,1,1] neg_lo:[0,1,0] neg_hi:[0,1,0]
	v_pk_fma_f32 v[26:27], v[14:15], v[80:81], v[26:27] op_sel:[0,0,0] op_sel_hi:[1,0,1]
	v_pk_fma_f32 v[18:19], v[66:67], v[22:23], v[42:43] op_sel:[0,0,0] op_sel_hi:[0,1,1] neg_lo:[0,1,0] neg_hi:[0,1,0]
	v_pk_fma_f32 v[26:27], v[16:17], v[80:81], v[26:27] op_sel:[0,1,0] op_sel_hi:[1,1,1]
	v_pk_fma_f32 v[20:21], v[66:67], v[22:23], v[44:45] op_sel:[1,0,0] op_sel_hi:[1,1,1] neg_lo:[0,1,0] neg_hi:[0,1,0]
	v_pk_fma_f32 v[26:27], v[18:19], v[82:83], v[26:27] op_sel:[0,0,0] op_sel_hi:[1,0,1]
	ds_write_b32 v49, v46 offset:1152
	v_pk_fma_f32 v[26:27], v[20:21], v[82:83], v[26:27] op_sel:[0,1,0] op_sel_hi:[1,1,1]
	s_waitcnt lgkmcnt(5)
	v_pk_mul_f32 v[22:23], v[6:7], v[94:95] op_sel:[0,0] op_sel_hi:[1,0]
	v_pk_mul_f32 v[30:31], v[110:111], v[134:135] op_sel:[0,0] op_sel_hi:[0,1]
	ds_read_b128 v[52:55], v47 offset:3072
	v_pk_fma_f32 v[22:23], v[8:9], v[94:95], v[22:23] op_sel:[0,1,0] op_sel_hi:[1,1,1]
	v_pk_mul_f32 v[32:33], v[110:111], v[134:135] op_sel:[1,0] op_sel_hi:[1,1]
	ds_read_b128 v[56:59], v47 offset:3088
	v_pk_fma_f32 v[22:23], v[10:11], v[96:97], v[22:23] op_sel:[0,0,0] op_sel_hi:[1,0,1]
	v_pk_mul_f32 v[34:35], v[112:113], v[134:135] op_sel:[0,0] op_sel_hi:[0,1]
	ds_read_b128 v[68:71], v47 offset:11264
	v_pk_fma_f32 v[22:23], v[12:13], v[96:97], v[22:23] op_sel:[0,1,0] op_sel_hi:[1,1,1]
	v_pk_mul_f32 v[36:37], v[112:113], v[134:135] op_sel:[1,0] op_sel_hi:[1,1]
	ds_read_b128 v[72:75], v47 offset:11280
	v_pk_fma_f32 v[22:23], v[14:15], v[98:99], v[22:23] op_sel:[0,0,0] op_sel_hi:[1,0,1]
	v_pk_mul_f32 v[38:39], v[114:115], v[134:135] op_sel:[0,0] op_sel_hi:[0,1]
	ds_read_b64 v[92:93], v48 offset:3072
	v_pk_fma_f32 v[22:23], v[16:17], v[98:99], v[22:23] op_sel:[0,1,0] op_sel_hi:[1,1,1]
	v_pk_mul_f32 v[40:41], v[114:115], v[134:135] op_sel:[1,0] op_sel_hi:[1,1]
	ds_read_b128 v[84:87], v47 offset:19456
	v_pk_fma_f32 v[22:23], v[18:19], v[100:101], v[22:23] op_sel:[0,0,0] op_sel_hi:[1,0,1]
	v_pk_mul_f32 v[42:43], v[116:117], v[134:135] op_sel:[0,0] op_sel_hi:[0,1]
	ds_read_b128 v[88:91], v47 offset:19472
	v_pk_fma_f32 v[22:23], v[20:21], v[100:101], v[22:23] op_sel:[0,1,0] op_sel_hi:[1,1,1]
	v_pk_mul_f32 v[44:45], v[116:117], v[134:135] op_sel:[1,0] op_sel_hi:[1,1]
	ds_read_b128 v[60:63], v47 offset:7168
	v_pk_fma_f32 v[30:31], v[126:127], v[6:7], v[30:31] op_sel:[0,0,0] op_sel_hi:[0,1,1]
	v_pk_fma_f32 v[32:33], v[126:127], v[8:9], v[32:33] op_sel:[1,0,0] op_sel_hi:[1,1,1]
	ds_read_b128 v[64:67], v47 offset:7184
	v_pk_fma_f32 v[34:35], v[128:129], v[10:11], v[34:35] op_sel:[0,0,0] op_sel_hi:[0,1,1]
	v_pk_fma_f32 v[36:37], v[128:129], v[12:13], v[36:37] op_sel:[1,0,0] op_sel_hi:[1,1,1]
	ds_read_b128 v[76:79], v47 offset:15360
	v_add_f32_dpp v22, v22, v22 quad_perm:[1,0,3,2] row_mask:0xf bank_mask:0xf
	v_add_f32_dpp v23, v23, v23 quad_perm:[1,0,3,2] row_mask:0xf bank_mask:0xf
	ds_read_b128 v[80:83], v47 offset:15376
	v_add_f32_dpp v26, v26, v26 quad_perm:[1,0,3,2] row_mask:0xf bank_mask:0xf
	v_add_f32_dpp v27, v27, v27 quad_perm:[1,0,3,2] row_mask:0xf bank_mask:0xf
	v_pk_fma_f32 v[38:39], v[130:131], v[14:15], v[38:39] op_sel:[0,0,0] op_sel_hi:[0,1,1]
	v_pk_fma_f32 v[40:41], v[130:131], v[16:17], v[40:41] op_sel:[1,0,0] op_sel_hi:[1,1,1]
	v_add_f32_dpp v22, v22, v22 quad_perm:[2,3,0,1] row_mask:0xf bank_mask:0xf
	v_add_f32_dpp v23, v23, v23 quad_perm:[2,3,0,1] row_mask:0xf bank_mask:0xf
	v_add_f32_dpp v26, v26, v26 quad_perm:[2,3,0,1] row_mask:0xf bank_mask:0xf
	v_add_f32_dpp v27, v27, v27 quad_perm:[2,3,0,1] row_mask:0xf bank_mask:0xf
	v_pk_fma_f32 v[42:43], v[132:133], v[18:19], v[42:43] op_sel:[0,0,0] op_sel_hi:[0,1,1]
	v_pk_fma_f32 v[44:45], v[132:133], v[20:21], v[44:45] op_sel:[1,0,0] op_sel_hi:[1,1,1]
	v_add_f32_dpp v22, v22, v22 row_half_mirror row_mask:0xf bank_mask:0xf
	v_add_f32_dpp v23, v23, v23 row_half_mirror row_mask:0xf bank_mask:0xf
	v_add_f32_dpp v26, v26, v26 row_half_mirror row_mask:0xf bank_mask:0xf
	v_add_f32_dpp v27, v27, v27 row_half_mirror row_mask:0xf bank_mask:0xf
	s_waitcnt lgkmcnt(12)
	v_pk_fma_f32 v[6:7], v[102:103], v[22:23], v[30:31] op_sel:[0,0,0] op_sel_hi:[0,1,1] neg_lo:[0,1,0] neg_hi:[0,1,0]
	v_cvt_pk_f16_f32 v46, v26, v27
	v_pk_fma_f32 v[8:9], v[102:103], v[22:23], v[32:33] op_sel:[1,0,0] op_sel_hi:[1,1,1] neg_lo:[0,1,0] neg_hi:[0,1,0]
	v_pk_mul_f32 v[26:27], v[6:7], v[118:119] op_sel:[0,0] op_sel_hi:[1,0]
	v_pk_fma_f32 v[10:11], v[104:105], v[22:23], v[34:35] op_sel:[0,0,0] op_sel_hi:[0,1,1] neg_lo:[0,1,0] neg_hi:[0,1,0]
	v_pk_fma_f32 v[26:27], v[8:9], v[118:119], v[26:27] op_sel:[0,1,0] op_sel_hi:[1,1,1]
	v_pk_fma_f32 v[12:13], v[104:105], v[22:23], v[36:37] op_sel:[1,0,0] op_sel_hi:[1,1,1] neg_lo:[0,1,0] neg_hi:[0,1,0]
	v_pk_fma_f32 v[26:27], v[10:11], v[120:121], v[26:27] op_sel:[0,0,0] op_sel_hi:[1,0,1]
	v_pk_fma_f32 v[14:15], v[106:107], v[22:23], v[38:39] op_sel:[0,0,0] op_sel_hi:[0,1,1] neg_lo:[0,1,0] neg_hi:[0,1,0]
	v_pk_fma_f32 v[26:27], v[12:13], v[120:121], v[26:27] op_sel:[0,1,0] op_sel_hi:[1,1,1]
	v_pk_fma_f32 v[16:17], v[106:107], v[22:23], v[40:41] op_sel:[1,0,0] op_sel_hi:[1,1,1] neg_lo:[0,1,0] neg_hi:[0,1,0]
	v_pk_fma_f32 v[26:27], v[14:15], v[122:123], v[26:27] op_sel:[0,0,0] op_sel_hi:[1,0,1]
	v_pk_fma_f32 v[18:19], v[108:109], v[22:23], v[42:43] op_sel:[0,0,0] op_sel_hi:[0,1,1] neg_lo:[0,1,0] neg_hi:[0,1,0]
	v_pk_fma_f32 v[26:27], v[16:17], v[122:123], v[26:27] op_sel:[0,1,0] op_sel_hi:[1,1,1]
	v_pk_fma_f32 v[20:21], v[108:109], v[22:23], v[44:45] op_sel:[1,0,0] op_sel_hi:[1,1,1] neg_lo:[0,1,0] neg_hi:[0,1,0]
	v_pk_fma_f32 v[26:27], v[18:19], v[124:125], v[26:27] op_sel:[0,0,0] op_sel_hi:[1,0,1]
	ds_write_b32 v49, v46 offset:1280
	v_pk_fma_f32 v[26:27], v[20:21], v[124:125], v[26:27] op_sel:[0,1,0] op_sel_hi:[1,1,1]
	s_waitcnt lgkmcnt(5)
	v_pk_mul_f32 v[22:23], v[6:7], v[52:53] op_sel:[0,0] op_sel_hi:[1,0]
	v_pk_mul_f32 v[30:31], v[68:69], v[92:93] op_sel:[0,0] op_sel_hi:[0,1]
	ds_read_b128 v[94:97], v47 offset:3328
	v_pk_fma_f32 v[22:23], v[8:9], v[52:53], v[22:23] op_sel:[0,1,0] op_sel_hi:[1,1,1]
	v_pk_mul_f32 v[32:33], v[68:69], v[92:93] op_sel:[1,0] op_sel_hi:[1,1]
	ds_read_b128 v[98:101], v47 offset:3344
	v_pk_fma_f32 v[22:23], v[10:11], v[54:55], v[22:23] op_sel:[0,0,0] op_sel_hi:[1,0,1]
	v_pk_mul_f32 v[34:35], v[70:71], v[92:93] op_sel:[0,0] op_sel_hi:[0,1]
	ds_read_b128 v[110:113], v47 offset:11520
	v_pk_fma_f32 v[22:23], v[12:13], v[54:55], v[22:23] op_sel:[0,1,0] op_sel_hi:[1,1,1]
	v_pk_mul_f32 v[36:37], v[70:71], v[92:93] op_sel:[1,0] op_sel_hi:[1,1]
	ds_read_b128 v[114:117], v47 offset:11536
	v_pk_fma_f32 v[22:23], v[14:15], v[56:57], v[22:23] op_sel:[0,0,0] op_sel_hi:[1,0,1]
	v_pk_mul_f32 v[38:39], v[72:73], v[92:93] op_sel:[0,0] op_sel_hi:[0,1]
	ds_read_b64 v[134:135], v48 offset:3328
	v_pk_fma_f32 v[22:23], v[16:17], v[56:57], v[22:23] op_sel:[0,1,0] op_sel_hi:[1,1,1]
	v_pk_mul_f32 v[40:41], v[72:73], v[92:93] op_sel:[1,0] op_sel_hi:[1,1]
	ds_read_b128 v[126:129], v47 offset:19712
	v_pk_fma_f32 v[22:23], v[18:19], v[58:59], v[22:23] op_sel:[0,0,0] op_sel_hi:[1,0,1]
	v_pk_mul_f32 v[42:43], v[74:75], v[92:93] op_sel:[0,0] op_sel_hi:[0,1]
	ds_read_b128 v[130:133], v47 offset:19728
	v_pk_fma_f32 v[22:23], v[20:21], v[58:59], v[22:23] op_sel:[0,1,0] op_sel_hi:[1,1,1]
	v_pk_mul_f32 v[44:45], v[74:75], v[92:93] op_sel:[1,0] op_sel_hi:[1,1]
	ds_read_b128 v[102:105], v47 offset:7424
	v_pk_fma_f32 v[30:31], v[84:85], v[6:7], v[30:31] op_sel:[0,0,0] op_sel_hi:[0,1,1]
	v_pk_fma_f32 v[32:33], v[84:85], v[8:9], v[32:33] op_sel:[1,0,0] op_sel_hi:[1,1,1]
	ds_read_b128 v[106:109], v47 offset:7440
	v_pk_fma_f32 v[34:35], v[86:87], v[10:11], v[34:35] op_sel:[0,0,0] op_sel_hi:[0,1,1]
	v_pk_fma_f32 v[36:37], v[86:87], v[12:13], v[36:37] op_sel:[1,0,0] op_sel_hi:[1,1,1]
	ds_read_b128 v[118:121], v47 offset:15616
	v_add_f32_dpp v22, v22, v22 quad_perm:[1,0,3,2] row_mask:0xf bank_mask:0xf
	v_add_f32_dpp v23, v23, v23 quad_perm:[1,0,3,2] row_mask:0xf bank_mask:0xf
	ds_read_b128 v[122:125], v47 offset:15632
	v_add_f32_dpp v26, v26, v26 quad_perm:[1,0,3,2] row_mask:0xf bank_mask:0xf
	v_add_f32_dpp v27, v27, v27 quad_perm:[1,0,3,2] row_mask:0xf bank_mask:0xf
	v_pk_fma_f32 v[38:39], v[88:89], v[14:15], v[38:39] op_sel:[0,0,0] op_sel_hi:[0,1,1]
	v_pk_fma_f32 v[40:41], v[88:89], v[16:17], v[40:41] op_sel:[1,0,0] op_sel_hi:[1,1,1]
	v_add_f32_dpp v22, v22, v22 quad_perm:[2,3,0,1] row_mask:0xf bank_mask:0xf
	v_add_f32_dpp v23, v23, v23 quad_perm:[2,3,0,1] row_mask:0xf bank_mask:0xf
	v_add_f32_dpp v26, v26, v26 quad_perm:[2,3,0,1] row_mask:0xf bank_mask:0xf
	v_add_f32_dpp v27, v27, v27 quad_perm:[2,3,0,1] row_mask:0xf bank_mask:0xf
	v_pk_fma_f32 v[42:43], v[90:91], v[18:19], v[42:43] op_sel:[0,0,0] op_sel_hi:[0,1,1]
	v_pk_fma_f32 v[44:45], v[90:91], v[20:21], v[44:45] op_sel:[1,0,0] op_sel_hi:[1,1,1]
	v_add_f32_dpp v22, v22, v22 row_half_mirror row_mask:0xf bank_mask:0xf
	v_add_f32_dpp v23, v23, v23 row_half_mirror row_mask:0xf bank_mask:0xf
	v_add_f32_dpp v26, v26, v26 row_half_mirror row_mask:0xf bank_mask:0xf
	v_add_f32_dpp v27, v27, v27 row_half_mirror row_mask:0xf bank_mask:0xf
	s_waitcnt lgkmcnt(12)
	v_pk_fma_f32 v[6:7], v[60:61], v[22:23], v[30:31] op_sel:[0,0,0] op_sel_hi:[0,1,1] neg_lo:[0,1,0] neg_hi:[0,1,0]
	v_cvt_pk_f16_f32 v46, v26, v27
	v_pk_fma_f32 v[8:9], v[60:61], v[22:23], v[32:33] op_sel:[1,0,0] op_sel_hi:[1,1,1] neg_lo:[0,1,0] neg_hi:[0,1,0]
	v_pk_mul_f32 v[26:27], v[6:7], v[76:77] op_sel:[0,0] op_sel_hi:[1,0]
	v_pk_fma_f32 v[10:11], v[62:63], v[22:23], v[34:35] op_sel:[0,0,0] op_sel_hi:[0,1,1] neg_lo:[0,1,0] neg_hi:[0,1,0]
	v_pk_fma_f32 v[26:27], v[8:9], v[76:77], v[26:27] op_sel:[0,1,0] op_sel_hi:[1,1,1]
	v_pk_fma_f32 v[12:13], v[62:63], v[22:23], v[36:37] op_sel:[1,0,0] op_sel_hi:[1,1,1] neg_lo:[0,1,0] neg_hi:[0,1,0]
	v_pk_fma_f32 v[26:27], v[10:11], v[78:79], v[26:27] op_sel:[0,0,0] op_sel_hi:[1,0,1]
	v_pk_fma_f32 v[14:15], v[64:65], v[22:23], v[38:39] op_sel:[0,0,0] op_sel_hi:[0,1,1] neg_lo:[0,1,0] neg_hi:[0,1,0]
	v_pk_fma_f32 v[26:27], v[12:13], v[78:79], v[26:27] op_sel:[0,1,0] op_sel_hi:[1,1,1]
	v_pk_fma_f32 v[16:17], v[64:65], v[22:23], v[40:41] op_sel:[1,0,0] op_sel_hi:[1,1,1] neg_lo:[0,1,0] neg_hi:[0,1,0]
	v_pk_fma_f32 v[26:27], v[14:15], v[80:81], v[26:27] op_sel:[0,0,0] op_sel_hi:[1,0,1]
	v_pk_fma_f32 v[18:19], v[66:67], v[22:23], v[42:43] op_sel:[0,0,0] op_sel_hi:[0,1,1] neg_lo:[0,1,0] neg_hi:[0,1,0]
	v_pk_fma_f32 v[26:27], v[16:17], v[80:81], v[26:27] op_sel:[0,1,0] op_sel_hi:[1,1,1]
	v_pk_fma_f32 v[20:21], v[66:67], v[22:23], v[44:45] op_sel:[1,0,0] op_sel_hi:[1,1,1] neg_lo:[0,1,0] neg_hi:[0,1,0]
	v_pk_fma_f32 v[26:27], v[18:19], v[82:83], v[26:27] op_sel:[0,0,0] op_sel_hi:[1,0,1]
	ds_write_b32 v49, v46 offset:1408
	v_pk_fma_f32 v[26:27], v[20:21], v[82:83], v[26:27] op_sel:[0,1,0] op_sel_hi:[1,1,1]
	s_waitcnt lgkmcnt(5)
	v_pk_mul_f32 v[22:23], v[6:7], v[94:95] op_sel:[0,0] op_sel_hi:[1,0]
	v_pk_mul_f32 v[30:31], v[110:111], v[134:135] op_sel:[0,0] op_sel_hi:[0,1]
	ds_read_b128 v[52:55], v47 offset:3584
	v_pk_fma_f32 v[22:23], v[8:9], v[94:95], v[22:23] op_sel:[0,1,0] op_sel_hi:[1,1,1]
	v_pk_mul_f32 v[32:33], v[110:111], v[134:135] op_sel:[1,0] op_sel_hi:[1,1]
	ds_read_b128 v[56:59], v47 offset:3600
	v_pk_fma_f32 v[22:23], v[10:11], v[96:97], v[22:23] op_sel:[0,0,0] op_sel_hi:[1,0,1]
	v_pk_mul_f32 v[34:35], v[112:113], v[134:135] op_sel:[0,0] op_sel_hi:[0,1]
	ds_read_b128 v[68:71], v47 offset:11776
	v_pk_fma_f32 v[22:23], v[12:13], v[96:97], v[22:23] op_sel:[0,1,0] op_sel_hi:[1,1,1]
	v_pk_mul_f32 v[36:37], v[112:113], v[134:135] op_sel:[1,0] op_sel_hi:[1,1]
	ds_read_b128 v[72:75], v47 offset:11792
	v_pk_fma_f32 v[22:23], v[14:15], v[98:99], v[22:23] op_sel:[0,0,0] op_sel_hi:[1,0,1]
	v_pk_mul_f32 v[38:39], v[114:115], v[134:135] op_sel:[0,0] op_sel_hi:[0,1]
	ds_read_b64 v[92:93], v48 offset:3584
	v_pk_fma_f32 v[22:23], v[16:17], v[98:99], v[22:23] op_sel:[0,1,0] op_sel_hi:[1,1,1]
	v_pk_mul_f32 v[40:41], v[114:115], v[134:135] op_sel:[1,0] op_sel_hi:[1,1]
	ds_read_b128 v[84:87], v47 offset:19968
	v_pk_fma_f32 v[22:23], v[18:19], v[100:101], v[22:23] op_sel:[0,0,0] op_sel_hi:[1,0,1]
	v_pk_mul_f32 v[42:43], v[116:117], v[134:135] op_sel:[0,0] op_sel_hi:[0,1]
	ds_read_b128 v[88:91], v47 offset:19984
	v_pk_fma_f32 v[22:23], v[20:21], v[100:101], v[22:23] op_sel:[0,1,0] op_sel_hi:[1,1,1]
	v_pk_mul_f32 v[44:45], v[116:117], v[134:135] op_sel:[1,0] op_sel_hi:[1,1]
	ds_read_b128 v[60:63], v47 offset:7680
	v_pk_fma_f32 v[30:31], v[126:127], v[6:7], v[30:31] op_sel:[0,0,0] op_sel_hi:[0,1,1]
	v_pk_fma_f32 v[32:33], v[126:127], v[8:9], v[32:33] op_sel:[1,0,0] op_sel_hi:[1,1,1]
	ds_read_b128 v[64:67], v47 offset:7696
	v_pk_fma_f32 v[34:35], v[128:129], v[10:11], v[34:35] op_sel:[0,0,0] op_sel_hi:[0,1,1]
	v_pk_fma_f32 v[36:37], v[128:129], v[12:13], v[36:37] op_sel:[1,0,0] op_sel_hi:[1,1,1]
	ds_read_b128 v[76:79], v47 offset:15872
	v_add_f32_dpp v22, v22, v22 quad_perm:[1,0,3,2] row_mask:0xf bank_mask:0xf
	v_add_f32_dpp v23, v23, v23 quad_perm:[1,0,3,2] row_mask:0xf bank_mask:0xf
	ds_read_b128 v[80:83], v47 offset:15888
	v_add_f32_dpp v26, v26, v26 quad_perm:[1,0,3,2] row_mask:0xf bank_mask:0xf
	v_add_f32_dpp v27, v27, v27 quad_perm:[1,0,3,2] row_mask:0xf bank_mask:0xf
	v_pk_fma_f32 v[38:39], v[130:131], v[14:15], v[38:39] op_sel:[0,0,0] op_sel_hi:[0,1,1]
	v_pk_fma_f32 v[40:41], v[130:131], v[16:17], v[40:41] op_sel:[1,0,0] op_sel_hi:[1,1,1]
	v_add_f32_dpp v22, v22, v22 quad_perm:[2,3,0,1] row_mask:0xf bank_mask:0xf
	v_add_f32_dpp v23, v23, v23 quad_perm:[2,3,0,1] row_mask:0xf bank_mask:0xf
	v_add_f32_dpp v26, v26, v26 quad_perm:[2,3,0,1] row_mask:0xf bank_mask:0xf
	v_add_f32_dpp v27, v27, v27 quad_perm:[2,3,0,1] row_mask:0xf bank_mask:0xf
	v_pk_fma_f32 v[42:43], v[132:133], v[18:19], v[42:43] op_sel:[0,0,0] op_sel_hi:[0,1,1]
	v_pk_fma_f32 v[44:45], v[132:133], v[20:21], v[44:45] op_sel:[1,0,0] op_sel_hi:[1,1,1]
	v_add_f32_dpp v22, v22, v22 row_half_mirror row_mask:0xf bank_mask:0xf
	v_add_f32_dpp v23, v23, v23 row_half_mirror row_mask:0xf bank_mask:0xf
	v_add_f32_dpp v26, v26, v26 row_half_mirror row_mask:0xf bank_mask:0xf
	v_add_f32_dpp v27, v27, v27 row_half_mirror row_mask:0xf bank_mask:0xf
	s_waitcnt lgkmcnt(12)
	v_pk_fma_f32 v[6:7], v[102:103], v[22:23], v[30:31] op_sel:[0,0,0] op_sel_hi:[0,1,1] neg_lo:[0,1,0] neg_hi:[0,1,0]
	v_cvt_pk_f16_f32 v46, v26, v27
	v_pk_fma_f32 v[8:9], v[102:103], v[22:23], v[32:33] op_sel:[1,0,0] op_sel_hi:[1,1,1] neg_lo:[0,1,0] neg_hi:[0,1,0]
	v_pk_mul_f32 v[26:27], v[6:7], v[118:119] op_sel:[0,0] op_sel_hi:[1,0]
	v_pk_fma_f32 v[10:11], v[104:105], v[22:23], v[34:35] op_sel:[0,0,0] op_sel_hi:[0,1,1] neg_lo:[0,1,0] neg_hi:[0,1,0]
	v_pk_fma_f32 v[26:27], v[8:9], v[118:119], v[26:27] op_sel:[0,1,0] op_sel_hi:[1,1,1]
	v_pk_fma_f32 v[12:13], v[104:105], v[22:23], v[36:37] op_sel:[1,0,0] op_sel_hi:[1,1,1] neg_lo:[0,1,0] neg_hi:[0,1,0]
	v_pk_fma_f32 v[26:27], v[10:11], v[120:121], v[26:27] op_sel:[0,0,0] op_sel_hi:[1,0,1]
	v_pk_fma_f32 v[14:15], v[106:107], v[22:23], v[38:39] op_sel:[0,0,0] op_sel_hi:[0,1,1] neg_lo:[0,1,0] neg_hi:[0,1,0]
	v_pk_fma_f32 v[26:27], v[12:13], v[120:121], v[26:27] op_sel:[0,1,0] op_sel_hi:[1,1,1]
	v_pk_fma_f32 v[16:17], v[106:107], v[22:23], v[40:41] op_sel:[1,0,0] op_sel_hi:[1,1,1] neg_lo:[0,1,0] neg_hi:[0,1,0]
	v_pk_fma_f32 v[26:27], v[14:15], v[122:123], v[26:27] op_sel:[0,0,0] op_sel_hi:[1,0,1]
	v_pk_fma_f32 v[18:19], v[108:109], v[22:23], v[42:43] op_sel:[0,0,0] op_sel_hi:[0,1,1] neg_lo:[0,1,0] neg_hi:[0,1,0]
	v_pk_fma_f32 v[26:27], v[16:17], v[122:123], v[26:27] op_sel:[0,1,0] op_sel_hi:[1,1,1]
	v_pk_fma_f32 v[20:21], v[108:109], v[22:23], v[44:45] op_sel:[1,0,0] op_sel_hi:[1,1,1] neg_lo:[0,1,0] neg_hi:[0,1,0]
	v_pk_fma_f32 v[26:27], v[18:19], v[124:125], v[26:27] op_sel:[0,0,0] op_sel_hi:[1,0,1]
	ds_write_b32 v49, v46 offset:1536
	v_pk_fma_f32 v[26:27], v[20:21], v[124:125], v[26:27] op_sel:[0,1,0] op_sel_hi:[1,1,1]
	s_waitcnt lgkmcnt(5)
	v_pk_mul_f32 v[22:23], v[6:7], v[52:53] op_sel:[0,0] op_sel_hi:[1,0]
	v_pk_mul_f32 v[30:31], v[68:69], v[92:93] op_sel:[0,0] op_sel_hi:[0,1]
	ds_read_b128 v[94:97], v47 offset:3840
	v_pk_fma_f32 v[22:23], v[8:9], v[52:53], v[22:23] op_sel:[0,1,0] op_sel_hi:[1,1,1]
	v_pk_mul_f32 v[32:33], v[68:69], v[92:93] op_sel:[1,0] op_sel_hi:[1,1]
	ds_read_b128 v[98:101], v47 offset:3856
	v_pk_fma_f32 v[22:23], v[10:11], v[54:55], v[22:23] op_sel:[0,0,0] op_sel_hi:[1,0,1]
	v_pk_mul_f32 v[34:35], v[70:71], v[92:93] op_sel:[0,0] op_sel_hi:[0,1]
	ds_read_b128 v[110:113], v47 offset:12032
	v_pk_fma_f32 v[22:23], v[12:13], v[54:55], v[22:23] op_sel:[0,1,0] op_sel_hi:[1,1,1]
	v_pk_mul_f32 v[36:37], v[70:71], v[92:93] op_sel:[1,0] op_sel_hi:[1,1]
	ds_read_b128 v[114:117], v47 offset:12048
	v_pk_fma_f32 v[22:23], v[14:15], v[56:57], v[22:23] op_sel:[0,0,0] op_sel_hi:[1,0,1]
	v_pk_mul_f32 v[38:39], v[72:73], v[92:93] op_sel:[0,0] op_sel_hi:[0,1]
	ds_read_b64 v[134:135], v48 offset:3840
	v_pk_fma_f32 v[22:23], v[16:17], v[56:57], v[22:23] op_sel:[0,1,0] op_sel_hi:[1,1,1]
	v_pk_mul_f32 v[40:41], v[72:73], v[92:93] op_sel:[1,0] op_sel_hi:[1,1]
	ds_read_b128 v[126:129], v47 offset:20224
	v_pk_fma_f32 v[22:23], v[18:19], v[58:59], v[22:23] op_sel:[0,0,0] op_sel_hi:[1,0,1]
	v_pk_mul_f32 v[42:43], v[74:75], v[92:93] op_sel:[0,0] op_sel_hi:[0,1]
	ds_read_b128 v[130:133], v47 offset:20240
	v_pk_fma_f32 v[22:23], v[20:21], v[58:59], v[22:23] op_sel:[0,1,0] op_sel_hi:[1,1,1]
	v_pk_mul_f32 v[44:45], v[74:75], v[92:93] op_sel:[1,0] op_sel_hi:[1,1]
	ds_read_b128 v[102:105], v47 offset:7936
	v_pk_fma_f32 v[30:31], v[84:85], v[6:7], v[30:31] op_sel:[0,0,0] op_sel_hi:[0,1,1]
	v_pk_fma_f32 v[32:33], v[84:85], v[8:9], v[32:33] op_sel:[1,0,0] op_sel_hi:[1,1,1]
	ds_read_b128 v[106:109], v47 offset:7952
	v_pk_fma_f32 v[34:35], v[86:87], v[10:11], v[34:35] op_sel:[0,0,0] op_sel_hi:[0,1,1]
	v_pk_fma_f32 v[36:37], v[86:87], v[12:13], v[36:37] op_sel:[1,0,0] op_sel_hi:[1,1,1]
	ds_read_b128 v[118:121], v47 offset:16128
	v_add_f32_dpp v22, v22, v22 quad_perm:[1,0,3,2] row_mask:0xf bank_mask:0xf
	v_add_f32_dpp v23, v23, v23 quad_perm:[1,0,3,2] row_mask:0xf bank_mask:0xf
	ds_read_b128 v[122:125], v47 offset:16144
	v_add_f32_dpp v26, v26, v26 quad_perm:[1,0,3,2] row_mask:0xf bank_mask:0xf
	v_add_f32_dpp v27, v27, v27 quad_perm:[1,0,3,2] row_mask:0xf bank_mask:0xf
	v_pk_fma_f32 v[38:39], v[88:89], v[14:15], v[38:39] op_sel:[0,0,0] op_sel_hi:[0,1,1]
	v_pk_fma_f32 v[40:41], v[88:89], v[16:17], v[40:41] op_sel:[1,0,0] op_sel_hi:[1,1,1]
	v_add_f32_dpp v22, v22, v22 quad_perm:[2,3,0,1] row_mask:0xf bank_mask:0xf
	v_add_f32_dpp v23, v23, v23 quad_perm:[2,3,0,1] row_mask:0xf bank_mask:0xf
	v_add_f32_dpp v26, v26, v26 quad_perm:[2,3,0,1] row_mask:0xf bank_mask:0xf
	v_add_f32_dpp v27, v27, v27 quad_perm:[2,3,0,1] row_mask:0xf bank_mask:0xf
	v_pk_fma_f32 v[42:43], v[90:91], v[18:19], v[42:43] op_sel:[0,0,0] op_sel_hi:[0,1,1]
	v_pk_fma_f32 v[44:45], v[90:91], v[20:21], v[44:45] op_sel:[1,0,0] op_sel_hi:[1,1,1]
	v_add_f32_dpp v22, v22, v22 row_half_mirror row_mask:0xf bank_mask:0xf
	v_add_f32_dpp v23, v23, v23 row_half_mirror row_mask:0xf bank_mask:0xf
	v_add_f32_dpp v26, v26, v26 row_half_mirror row_mask:0xf bank_mask:0xf
	v_add_f32_dpp v27, v27, v27 row_half_mirror row_mask:0xf bank_mask:0xf
	s_waitcnt lgkmcnt(12)
	v_pk_fma_f32 v[6:7], v[60:61], v[22:23], v[30:31] op_sel:[0,0,0] op_sel_hi:[0,1,1] neg_lo:[0,1,0] neg_hi:[0,1,0]
	v_cvt_pk_f16_f32 v46, v26, v27
	v_pk_fma_f32 v[8:9], v[60:61], v[22:23], v[32:33] op_sel:[1,0,0] op_sel_hi:[1,1,1] neg_lo:[0,1,0] neg_hi:[0,1,0]
	v_pk_mul_f32 v[26:27], v[6:7], v[76:77] op_sel:[0,0] op_sel_hi:[1,0]
	v_pk_fma_f32 v[10:11], v[62:63], v[22:23], v[34:35] op_sel:[0,0,0] op_sel_hi:[0,1,1] neg_lo:[0,1,0] neg_hi:[0,1,0]
	v_pk_fma_f32 v[26:27], v[8:9], v[76:77], v[26:27] op_sel:[0,1,0] op_sel_hi:[1,1,1]
	v_pk_fma_f32 v[12:13], v[62:63], v[22:23], v[36:37] op_sel:[1,0,0] op_sel_hi:[1,1,1] neg_lo:[0,1,0] neg_hi:[0,1,0]
	v_pk_fma_f32 v[26:27], v[10:11], v[78:79], v[26:27] op_sel:[0,0,0] op_sel_hi:[1,0,1]
	v_pk_fma_f32 v[14:15], v[64:65], v[22:23], v[38:39] op_sel:[0,0,0] op_sel_hi:[0,1,1] neg_lo:[0,1,0] neg_hi:[0,1,0]
	v_pk_fma_f32 v[26:27], v[12:13], v[78:79], v[26:27] op_sel:[0,1,0] op_sel_hi:[1,1,1]
	v_pk_fma_f32 v[16:17], v[64:65], v[22:23], v[40:41] op_sel:[1,0,0] op_sel_hi:[1,1,1] neg_lo:[0,1,0] neg_hi:[0,1,0]
	v_pk_fma_f32 v[26:27], v[14:15], v[80:81], v[26:27] op_sel:[0,0,0] op_sel_hi:[1,0,1]
	v_pk_fma_f32 v[18:19], v[66:67], v[22:23], v[42:43] op_sel:[0,0,0] op_sel_hi:[0,1,1] neg_lo:[0,1,0] neg_hi:[0,1,0]
	v_pk_fma_f32 v[26:27], v[16:17], v[80:81], v[26:27] op_sel:[0,1,0] op_sel_hi:[1,1,1]
	v_pk_fma_f32 v[20:21], v[66:67], v[22:23], v[44:45] op_sel:[1,0,0] op_sel_hi:[1,1,1] neg_lo:[0,1,0] neg_hi:[0,1,0]
	v_pk_fma_f32 v[26:27], v[18:19], v[82:83], v[26:27] op_sel:[0,0,0] op_sel_hi:[1,0,1]
	ds_write_b32 v49, v46 offset:1664
	v_pk_fma_f32 v[26:27], v[20:21], v[82:83], v[26:27] op_sel:[0,1,0] op_sel_hi:[1,1,1]
	s_waitcnt lgkmcnt(5)
	v_pk_mul_f32 v[22:23], v[6:7], v[94:95] op_sel:[0,0] op_sel_hi:[1,0]
	v_pk_mul_f32 v[30:31], v[110:111], v[134:135] op_sel:[0,0] op_sel_hi:[0,1]
	v_pk_fma_f32 v[22:23], v[8:9], v[94:95], v[22:23] op_sel:[0,1,0] op_sel_hi:[1,1,1]
	v_pk_mul_f32 v[32:33], v[110:111], v[134:135] op_sel:[1,0] op_sel_hi:[1,1]
	v_pk_fma_f32 v[22:23], v[10:11], v[96:97], v[22:23] op_sel:[0,0,0] op_sel_hi:[1,0,1]
	v_pk_mul_f32 v[34:35], v[112:113], v[134:135] op_sel:[0,0] op_sel_hi:[0,1]
	v_pk_fma_f32 v[22:23], v[12:13], v[96:97], v[22:23] op_sel:[0,1,0] op_sel_hi:[1,1,1]
	v_pk_mul_f32 v[36:37], v[112:113], v[134:135] op_sel:[1,0] op_sel_hi:[1,1]
	v_pk_fma_f32 v[22:23], v[14:15], v[98:99], v[22:23] op_sel:[0,0,0] op_sel_hi:[1,0,1]
	v_pk_mul_f32 v[38:39], v[114:115], v[134:135] op_sel:[0,0] op_sel_hi:[0,1]
	v_pk_fma_f32 v[22:23], v[16:17], v[98:99], v[22:23] op_sel:[0,1,0] op_sel_hi:[1,1,1]
	v_pk_mul_f32 v[40:41], v[114:115], v[134:135] op_sel:[1,0] op_sel_hi:[1,1]
	v_pk_fma_f32 v[22:23], v[18:19], v[100:101], v[22:23] op_sel:[0,0,0] op_sel_hi:[1,0,1]
	v_pk_mul_f32 v[42:43], v[116:117], v[134:135] op_sel:[0,0] op_sel_hi:[0,1]
	v_pk_fma_f32 v[22:23], v[20:21], v[100:101], v[22:23] op_sel:[0,1,0] op_sel_hi:[1,1,1]
	v_pk_mul_f32 v[44:45], v[116:117], v[134:135] op_sel:[1,0] op_sel_hi:[1,1]
	v_pk_fma_f32 v[30:31], v[126:127], v[6:7], v[30:31] op_sel:[0,0,0] op_sel_hi:[0,1,1]
	v_pk_fma_f32 v[32:33], v[126:127], v[8:9], v[32:33] op_sel:[1,0,0] op_sel_hi:[1,1,1]
	v_pk_fma_f32 v[34:35], v[128:129], v[10:11], v[34:35] op_sel:[0,0,0] op_sel_hi:[0,1,1]
	v_pk_fma_f32 v[36:37], v[128:129], v[12:13], v[36:37] op_sel:[1,0,0] op_sel_hi:[1,1,1]
	v_add_f32_dpp v22, v22, v22 quad_perm:[1,0,3,2] row_mask:0xf bank_mask:0xf
	v_add_f32_dpp v23, v23, v23 quad_perm:[1,0,3,2] row_mask:0xf bank_mask:0xf
	v_add_f32_dpp v26, v26, v26 quad_perm:[1,0,3,2] row_mask:0xf bank_mask:0xf
	v_add_f32_dpp v27, v27, v27 quad_perm:[1,0,3,2] row_mask:0xf bank_mask:0xf
	v_pk_fma_f32 v[38:39], v[130:131], v[14:15], v[38:39] op_sel:[0,0,0] op_sel_hi:[0,1,1]
	v_pk_fma_f32 v[40:41], v[130:131], v[16:17], v[40:41] op_sel:[1,0,0] op_sel_hi:[1,1,1]
	v_add_f32_dpp v22, v22, v22 quad_perm:[2,3,0,1] row_mask:0xf bank_mask:0xf
	v_add_f32_dpp v23, v23, v23 quad_perm:[2,3,0,1] row_mask:0xf bank_mask:0xf
	v_add_f32_dpp v26, v26, v26 quad_perm:[2,3,0,1] row_mask:0xf bank_mask:0xf
	v_add_f32_dpp v27, v27, v27 quad_perm:[2,3,0,1] row_mask:0xf bank_mask:0xf
	v_pk_fma_f32 v[42:43], v[132:133], v[18:19], v[42:43] op_sel:[0,0,0] op_sel_hi:[0,1,1]
	v_pk_fma_f32 v[44:45], v[132:133], v[20:21], v[44:45] op_sel:[1,0,0] op_sel_hi:[1,1,1]
	v_add_f32_dpp v22, v22, v22 row_half_mirror row_mask:0xf bank_mask:0xf
	v_add_f32_dpp v23, v23, v23 row_half_mirror row_mask:0xf bank_mask:0xf
	v_add_f32_dpp v26, v26, v26 row_half_mirror row_mask:0xf bank_mask:0xf
	v_add_f32_dpp v27, v27, v27 row_half_mirror row_mask:0xf bank_mask:0xf
	s_waitcnt lgkmcnt(1)
	v_pk_fma_f32 v[6:7], v[102:103], v[22:23], v[30:31] op_sel:[0,0,0] op_sel_hi:[0,1,1] neg_lo:[0,1,0] neg_hi:[0,1,0]
	v_cvt_pk_f16_f32 v46, v26, v27
	v_pk_fma_f32 v[8:9], v[102:103], v[22:23], v[32:33] op_sel:[1,0,0] op_sel_hi:[1,1,1] neg_lo:[0,1,0] neg_hi:[0,1,0]
	v_pk_mul_f32 v[26:27], v[6:7], v[118:119] op_sel:[0,0] op_sel_hi:[1,0]
	v_pk_fma_f32 v[10:11], v[104:105], v[22:23], v[34:35] op_sel:[0,0,0] op_sel_hi:[0,1,1] neg_lo:[0,1,0] neg_hi:[0,1,0]
	v_pk_fma_f32 v[26:27], v[8:9], v[118:119], v[26:27] op_sel:[0,1,0] op_sel_hi:[1,1,1]
	v_pk_fma_f32 v[12:13], v[104:105], v[22:23], v[36:37] op_sel:[1,0,0] op_sel_hi:[1,1,1] neg_lo:[0,1,0] neg_hi:[0,1,0]
	v_pk_fma_f32 v[26:27], v[10:11], v[120:121], v[26:27] op_sel:[0,0,0] op_sel_hi:[1,0,1]
	v_pk_fma_f32 v[14:15], v[106:107], v[22:23], v[38:39] op_sel:[0,0,0] op_sel_hi:[0,1,1] neg_lo:[0,1,0] neg_hi:[0,1,0]
	v_pk_fma_f32 v[26:27], v[12:13], v[120:121], v[26:27] op_sel:[0,1,0] op_sel_hi:[1,1,1]
	v_pk_fma_f32 v[16:17], v[106:107], v[22:23], v[40:41] op_sel:[1,0,0] op_sel_hi:[1,1,1] neg_lo:[0,1,0] neg_hi:[0,1,0]
	v_pk_fma_f32 v[26:27], v[14:15], v[122:123], v[26:27] op_sel:[0,0,0] op_sel_hi:[1,0,1]
	v_pk_fma_f32 v[18:19], v[108:109], v[22:23], v[42:43] op_sel:[0,0,0] op_sel_hi:[0,1,1] neg_lo:[0,1,0] neg_hi:[0,1,0]
	v_pk_fma_f32 v[26:27], v[16:17], v[122:123], v[26:27] op_sel:[0,1,0] op_sel_hi:[1,1,1]
	v_pk_fma_f32 v[20:21], v[108:109], v[22:23], v[44:45] op_sel:[1,0,0] op_sel_hi:[1,1,1] neg_lo:[0,1,0] neg_hi:[0,1,0]
	v_pk_fma_f32 v[26:27], v[18:19], v[124:125], v[26:27] op_sel:[0,0,0] op_sel_hi:[1,0,1]
	ds_write_b32 v49, v46 offset:1792
	v_pk_fma_f32 v[26:27], v[20:21], v[124:125], v[26:27] op_sel:[0,1,0] op_sel_hi:[1,1,1]
	s_nop 1
	v_add_f32_dpp v26, v26, v26 quad_perm:[1,0,3,2] row_mask:0xf bank_mask:0xf
	v_add_f32_dpp v27, v27, v27 quad_perm:[1,0,3,2] row_mask:0xf bank_mask:0xf
	s_nop 0
	v_add_f32_dpp v26, v26, v26 quad_perm:[2,3,0,1] row_mask:0xf bank_mask:0xf
	v_add_f32_dpp v27, v27, v27 quad_perm:[2,3,0,1] row_mask:0xf bank_mask:0xf
	s_nop 0
	v_add_f32_dpp v26, v26, v26 row_half_mirror row_mask:0xf bank_mask:0xf
	v_add_f32_dpp v27, v27, v27 row_half_mirror row_mask:0xf bank_mask:0xf
	s_nop 0
	v_cvt_pk_f16_f32 v46, v26, v27
	s_nop 0
	ds_write_b32 v49, v46 offset:1920
	s_cmp_eq_u32 s38, 0
	s_cbranch_scc1 .Lsc_nofin
	s_cmp_lg_u32 s53, 15
	s_cbranch_scc1 .Lsc_nofin
	s_lshr_b32 s55, s33, 4
	s_lshl_b32 s55, s55, 1
	s_lshr_b32 s56, s43, 4
	s_add_u32 s55, s55, s56
	s_lshl_b32 s55, s55, 2
	s_lshr_b32 s56, s42, 1
	s_add_u32 s55, s55, s56
	s_cmp_eq_u32 s38, 0
	s_cselect_b32 s54, s42, s55
	s_lshl_b32 s54, s54, 1
	s_add_u32 s54, s54, s44
	s_lshl_b32 s54, s54, 1
	s_add_u32 s54, s54, s50
	s_lshl_b32 s54, s54, 4
	s_add_u32 s54, s54, s46
	s_lshl_b32 s54, s54, 14
	s_add_u32 s54, s54, 0xc000000
	s_add_u32 s30, s34, s54
	s_addc_u32 s31, s35, 0
	v_mov_b32_e32 v52, v6
	v_mov_b32_e32 v60, v7
	v_mov_b32_e32 v53, v8
	v_mov_b32_e32 v61, v9
	v_mov_b32_e32 v54, v10
	v_mov_b32_e32 v62, v11
	v_mov_b32_e32 v55, v12
	v_mov_b32_e32 v63, v13
	v_mov_b32_e32 v56, v14
	v_mov_b32_e32 v64, v15
	v_mov_b32_e32 v57, v16
	v_mov_b32_e32 v65, v17
	v_mov_b32_e32 v58, v18
	v_mov_b32_e32 v66, v19
	v_mov_b32_e32 v59, v20
	v_mov_b32_e32 v67, v21
	s_nop 0
	global_store_dwordx4 v3, v[52:55], s[30:31]
	global_store_dwordx4 v3, v[56:59], s[30:31] offset:16
	global_store_dwordx4 v3, v[60:63], s[30:31] offset:256
	global_store_dwordx4 v3, v[64:67], s[30:31] offset:272
